# b16 + EpiResid (DN0/WO/DN1): six second-half residual loads hoisted above first-half math/stores
# speedup vs baseline: 1.0037x; 1.0031x over previous
.LBB0_554:
	ds_read_b128 v[128:131], v190
	ds_read_b128 v[132:135], v190 offset:1024
	ds_read_b128 v[136:139], v190 offset:2048
	ds_read_b128 v[140:143], v190 offset:3072
	s_add_u32 s18, s14, 0x100
	s_addc_u32 s19, s15, 0
	s_cmp_eq_u32 s51, 40
	s_cselect_b32 s23, s1, s19
	s_cselect_b32 s22, s0, s18
	s_cselect_b32 s21, s7, s50
	s_cselect_b32 s20, s6, s49
	v_lshl_add_u64 v[184:185], s[14:15], 0, v[160:161]
	s_add_i32 m0, s34, 0xc000
	ds_read_b128 v[144:147], v191
	ds_read_b128 v[148:151], v191 offset:1024
	ds_read_b128 v[168:171], v191 offset:2048
	ds_read_b128 v[172:175], v191 offset:3072
	ds_read_b128 v[176:179], v191 offset:4096
	ds_read_b128 v[180:183], v191 offset:5120
	ds_read_b128 v[194:197], v191 offset:6144
	ds_read_b128 v[198:201], v191 offset:7168
	global_load_lds_dwordx4 v[184:185], off
	v_lshl_add_u64 v[184:185], s[14:15], 0, v[162:163]
	s_add_i32 m0, s34, 0xe000
	s_nop 0
	global_load_lds_dwordx4 v[184:185], off
	s_waitcnt lgkmcnt(8)
	s_barrier
	s_waitcnt lgkmcnt(0)
	s_setprio 1
	s_waitcnt lgkmcnt(0)
	v_mfma_f32_16x16x32_bf16 v[124:127], v[128:131], v[144:147], v[124:127]
	v_mfma_f32_16x16x32_bf16 v[120:123], v[136:139], v[144:147], v[120:123]
	v_mfma_f32_16x16x32_bf16 v[108:111], v[128:131], v[168:171], v[108:111]
	v_mfma_f32_16x16x32_bf16 v[104:107], v[136:139], v[168:171], v[104:107]
	v_mfma_f32_16x16x32_bf16 v[92:95], v[128:131], v[176:179], v[92:95]
	v_mfma_f32_16x16x32_bf16 v[88:91], v[136:139], v[176:179], v[88:91]
	v_mfma_f32_16x16x32_bf16 v[76:79], v[128:131], v[194:197], v[76:79]
	v_mfma_f32_16x16x32_bf16 v[72:75], v[136:139], v[194:197], v[72:75]
	v_mfma_f32_16x16x32_bf16 v[124:127], v[132:135], v[148:151], v[124:127]
	v_mfma_f32_16x16x32_bf16 v[120:123], v[140:143], v[148:151], v[120:123]
	v_mfma_f32_16x16x32_bf16 v[108:111], v[132:135], v[172:175], v[108:111]
	v_mfma_f32_16x16x32_bf16 v[104:107], v[140:143], v[172:175], v[104:107]
	v_mfma_f32_16x16x32_bf16 v[92:95], v[132:135], v[180:183], v[92:95]
	v_mfma_f32_16x16x32_bf16 v[88:91], v[140:143], v[180:183], v[88:91]
	v_mfma_f32_16x16x32_bf16 v[76:79], v[132:135], v[198:201], v[76:79]
	v_mfma_f32_16x16x32_bf16 v[72:75], v[140:143], v[198:201], v[72:75]
	s_setprio 0
	s_barrier
	s_add_i32 s14, s43, s31
	v_lshl_add_u64 v[184:185], s[20:21], 0, v[154:155]
	s_mov_b32 m0, s14
	ds_read_b128 v[202:205], v192
	ds_read_b128 v[206:209], v192 offset:1024
	ds_read_b128 v[210:213], v192 offset:2048
	ds_read_b128 v[214:217], v192 offset:3072
	global_load_lds_dwordx4 v[184:185], off
	v_lshl_add_u64 v[218:219], s[20:21], 0, v[158:159]
	s_add_i32 m0, s14, 0x2000
	s_nop 0
	global_load_lds_dwordx4 v[218:219], off
	s_barrier
	s_waitcnt lgkmcnt(0)
	s_setprio 1
	s_waitcnt lgkmcnt(0)
	v_mfma_f32_16x16x32_bf16 v[116:119], v[202:205], v[144:147], v[116:119]
	v_mfma_f32_16x16x32_bf16 v[112:115], v[210:213], v[144:147], v[112:115]
	v_mfma_f32_16x16x32_bf16 v[100:103], v[202:205], v[168:171], v[100:103]
	v_mfma_f32_16x16x32_bf16 v[96:99], v[210:213], v[168:171], v[96:99]
	v_mfma_f32_16x16x32_bf16 v[84:87], v[202:205], v[176:179], v[84:87]
	v_mfma_f32_16x16x32_bf16 v[80:83], v[210:213], v[176:179], v[80:83]
	v_mfma_f32_16x16x32_bf16 v[68:71], v[202:205], v[194:197], v[68:71]
	v_mfma_f32_16x16x32_bf16 v[64:67], v[210:213], v[194:197], v[64:67]
	v_mfma_f32_16x16x32_bf16 v[116:119], v[206:209], v[148:151], v[116:119]
	v_mfma_f32_16x16x32_bf16 v[112:115], v[214:217], v[148:151], v[112:115]
	v_mfma_f32_16x16x32_bf16 v[100:103], v[206:209], v[172:175], v[100:103]
	v_mfma_f32_16x16x32_bf16 v[96:99], v[214:217], v[172:175], v[96:99]
	v_mfma_f32_16x16x32_bf16 v[84:87], v[206:209], v[180:183], v[84:87]
	v_mfma_f32_16x16x32_bf16 v[80:83], v[214:217], v[180:183], v[80:83]
	v_mfma_f32_16x16x32_bf16 v[68:71], v[206:209], v[198:201], v[68:71]
	v_mfma_f32_16x16x32_bf16 v[64:67], v[214:217], v[198:201], v[64:67]
	s_setprio 0
	s_mov_b32 m0, s34
	v_lshl_add_u64 v[220:221], s[22:23], 0, v[152:153]
	s_barrier
	ds_read_b128 v[144:147], v191 offset:16384
	ds_read_b128 v[148:151], v191 offset:17408
	ds_read_b128 v[168:171], v191 offset:18432
	ds_read_b128 v[172:175], v191 offset:19456
	ds_read_b128 v[176:179], v191 offset:20480
	ds_read_b128 v[180:183], v191 offset:21504
	ds_read_b128 v[194:197], v191 offset:22528
	ds_read_b128 v[198:201], v191 offset:23552
	global_load_lds_dwordx4 v[220:221], off
	v_lshl_add_u64 v[222:223], s[22:23], 0, v[156:157]
	s_mov_b32 m0, s35
	s_nop 0
	global_load_lds_dwordx4 v[222:223], off
	s_barrier
	s_waitcnt lgkmcnt(0)
	s_setprio 1
	s_waitcnt lgkmcnt(0)
	v_mfma_f32_16x16x32_bf16 v[60:63], v[128:131], v[144:147], v[60:63]
	v_mfma_f32_16x16x32_bf16 v[56:59], v[136:139], v[144:147], v[56:59]
	v_mfma_f32_16x16x32_bf16 v[44:47], v[128:131], v[168:171], v[44:47]
	v_mfma_f32_16x16x32_bf16 v[40:43], v[136:139], v[168:171], v[40:43]
	v_mfma_f32_16x16x32_bf16 v[28:31], v[128:131], v[176:179], v[28:31]
	v_mfma_f32_16x16x32_bf16 v[24:27], v[136:139], v[176:179], v[24:27]
	v_mfma_f32_16x16x32_bf16 v[12:15], v[128:131], v[194:197], v[12:15]
	v_mfma_f32_16x16x32_bf16 v[8:11], v[136:139], v[194:197], v[8:11]
	v_mfma_f32_16x16x32_bf16 v[60:63], v[132:135], v[148:151], v[60:63]
	v_mfma_f32_16x16x32_bf16 v[56:59], v[140:143], v[148:151], v[56:59]
	v_mfma_f32_16x16x32_bf16 v[44:47], v[132:135], v[172:175], v[44:47]
	v_mfma_f32_16x16x32_bf16 v[40:43], v[140:143], v[172:175], v[40:43]
	v_mfma_f32_16x16x32_bf16 v[28:31], v[132:135], v[180:183], v[28:31]
	v_mfma_f32_16x16x32_bf16 v[24:27], v[140:143], v[180:183], v[24:27]
	v_mfma_f32_16x16x32_bf16 v[12:15], v[132:135], v[198:201], v[12:15]
	v_mfma_f32_16x16x32_bf16 v[8:11], v[140:143], v[198:201], v[8:11]
	s_setprio 0
	s_barrier
	s_add_u32 s14, s20, 0xb0000
	s_addc_u32 s15, s21, 0
	s_add_i32 s52, s44, s31
	v_lshl_add_u64 v[128:129], s[14:15], 0, v[154:155]
	s_mov_b32 m0, s52
	s_nop 0
	global_load_lds_dwordx4 v[128:129], off
	v_lshl_add_u64 v[128:129], s[14:15], 0, v[158:159]
	s_add_i32 m0, s52, 0x2000
	s_nop 0
	global_load_lds_dwordx4 v[128:129], off
	s_waitcnt vmcnt(6)
	s_barrier
	s_setprio 1
	v_mfma_f32_16x16x32_bf16 v[52:55], v[202:205], v[144:147], v[52:55]
	v_mfma_f32_16x16x32_bf16 v[48:51], v[210:213], v[144:147], v[48:51]
	v_mfma_f32_16x16x32_bf16 v[36:39], v[202:205], v[168:171], v[36:39]
	v_mfma_f32_16x16x32_bf16 v[32:35], v[210:213], v[168:171], v[32:35]
	v_mfma_f32_16x16x32_bf16 v[20:23], v[202:205], v[176:179], v[20:23]
	v_mfma_f32_16x16x32_bf16 v[16:19], v[210:213], v[176:179], v[16:19]
	v_mfma_f32_16x16x32_bf16 v[4:7], v[202:205], v[194:197], v[4:7]
	v_mfma_f32_16x16x32_bf16 v[0:3], v[210:213], v[194:197], v[0:3]
	v_mfma_f32_16x16x32_bf16 v[52:55], v[206:209], v[148:151], v[52:55]
	v_mfma_f32_16x16x32_bf16 v[48:51], v[214:217], v[148:151], v[48:51]
	v_mfma_f32_16x16x32_bf16 v[36:39], v[206:209], v[172:175], v[36:39]
	v_mfma_f32_16x16x32_bf16 v[32:35], v[214:217], v[172:175], v[32:35]
	v_mfma_f32_16x16x32_bf16 v[20:23], v[206:209], v[180:183], v[20:23]
	v_mfma_f32_16x16x32_bf16 v[16:19], v[214:217], v[180:183], v[16:19]
	v_mfma_f32_16x16x32_bf16 v[4:7], v[206:209], v[198:201], v[4:7]
	v_mfma_f32_16x16x32_bf16 v[0:3], v[214:217], v[198:201], v[0:3]
	s_setprio 0
	s_add_i32 s52, 0, 0x18000
	v_add_u32_e32 v140, s52, v187
	s_barrier
	ds_read_b128 v[128:131], v140
	ds_read_b128 v[132:135], v140 offset:1024
	ds_read_b128 v[136:139], v140 offset:2048
	ds_read_b128 v[140:143], v140 offset:3072
	s_add_u32 s14, s22, 0xb0000
	s_addc_u32 s15, s23, 0
	s_mov_b32 m0, s36
	v_lshl_add_u64 v[202:203], s[14:15], 0, v[152:153]
	ds_read_b128 v[144:147], v191 offset:32768
	ds_read_b128 v[148:151], v191 offset:33792
	ds_read_b128 v[168:171], v191 offset:34816
	ds_read_b128 v[172:175], v191 offset:35840
	ds_read_b128 v[176:179], v191 offset:36864
	ds_read_b128 v[180:183], v191 offset:37888
	ds_read_b128 v[194:197], v191 offset:38912
	ds_read_b128 v[198:201], v191 offset:39936
	global_load_lds_dwordx4 v[202:203], off
	v_lshl_add_u64 v[202:203], s[14:15], 0, v[156:157]
	s_mov_b32 m0, s37
	s_nop 0
	global_load_lds_dwordx4 v[202:203], off
	s_waitcnt lgkmcnt(8)
	s_barrier
	s_waitcnt lgkmcnt(0)
	s_setprio 1
	s_waitcnt lgkmcnt(0)
	v_mfma_f32_16x16x32_bf16 v[124:127], v[128:131], v[144:147], v[124:127]
	v_mfma_f32_16x16x32_bf16 v[120:123], v[136:139], v[144:147], v[120:123]
	v_mfma_f32_16x16x32_bf16 v[108:111], v[128:131], v[168:171], v[108:111]
	v_mfma_f32_16x16x32_bf16 v[104:107], v[136:139], v[168:171], v[104:107]
	v_mfma_f32_16x16x32_bf16 v[92:95], v[128:131], v[176:179], v[92:95]
	v_mfma_f32_16x16x32_bf16 v[88:91], v[136:139], v[176:179], v[88:91]
	v_mfma_f32_16x16x32_bf16 v[76:79], v[128:131], v[194:197], v[76:79]
	v_mfma_f32_16x16x32_bf16 v[72:75], v[136:139], v[194:197], v[72:75]
	v_mfma_f32_16x16x32_bf16 v[124:127], v[132:135], v[148:151], v[124:127]
	v_mfma_f32_16x16x32_bf16 v[120:123], v[140:143], v[148:151], v[120:123]
	v_mfma_f32_16x16x32_bf16 v[108:111], v[132:135], v[172:175], v[108:111]
	v_mfma_f32_16x16x32_bf16 v[104:107], v[140:143], v[172:175], v[104:107]
	v_mfma_f32_16x16x32_bf16 v[92:95], v[132:135], v[180:183], v[92:95]
	v_mfma_f32_16x16x32_bf16 v[88:91], v[140:143], v[180:183], v[88:91]
	v_mfma_f32_16x16x32_bf16 v[76:79], v[132:135], v[198:201], v[76:79]
	v_mfma_f32_16x16x32_bf16 v[72:75], v[140:143], v[198:201], v[72:75]
	s_setprio 0
	s_barrier
	s_add_i32 s22, 0, 0x1c000
	s_add_i32 s14, s52, s31
	v_add_u32_e32 v214, s22, v187
	v_lshl_add_u64 v[184:185], v[184:185], 0, s[12:13]
	s_mov_b32 m0, s14
	ds_read_b128 v[202:205], v214
	ds_read_b128 v[206:209], v214 offset:1024
	ds_read_b128 v[210:213], v214 offset:2048
	ds_read_b128 v[214:217], v214 offset:3072
	global_load_lds_dwordx4 v[184:185], off
	v_lshl_add_u64 v[184:185], v[218:219], 0, s[12:13]
	s_add_i32 m0, s14, 0x2000
	s_nop 0
	global_load_lds_dwordx4 v[184:185], off
	s_barrier
	s_waitcnt lgkmcnt(0)
	s_setprio 1
	s_waitcnt lgkmcnt(0)
	v_mfma_f32_16x16x32_bf16 v[116:119], v[202:205], v[144:147], v[116:119]
	v_mfma_f32_16x16x32_bf16 v[112:115], v[210:213], v[144:147], v[112:115]
	v_mfma_f32_16x16x32_bf16 v[100:103], v[202:205], v[168:171], v[100:103]
	v_mfma_f32_16x16x32_bf16 v[96:99], v[210:213], v[168:171], v[96:99]
	v_mfma_f32_16x16x32_bf16 v[84:87], v[202:205], v[176:179], v[84:87]
	v_mfma_f32_16x16x32_bf16 v[80:83], v[210:213], v[176:179], v[80:83]
	v_mfma_f32_16x16x32_bf16 v[68:71], v[202:205], v[194:197], v[68:71]
	v_mfma_f32_16x16x32_bf16 v[64:67], v[210:213], v[194:197], v[64:67]
	v_mfma_f32_16x16x32_bf16 v[116:119], v[206:209], v[148:151], v[116:119]
	v_mfma_f32_16x16x32_bf16 v[112:115], v[214:217], v[148:151], v[112:115]
	v_mfma_f32_16x16x32_bf16 v[100:103], v[206:209], v[172:175], v[100:103]
	v_mfma_f32_16x16x32_bf16 v[96:99], v[214:217], v[172:175], v[96:99]
	v_mfma_f32_16x16x32_bf16 v[84:87], v[206:209], v[180:183], v[84:87]
	v_mfma_f32_16x16x32_bf16 v[80:83], v[214:217], v[180:183], v[80:83]
	v_mfma_f32_16x16x32_bf16 v[68:71], v[206:209], v[198:201], v[68:71]
	v_mfma_f32_16x16x32_bf16 v[64:67], v[214:217], v[198:201], v[64:67]
	s_setprio 0
	s_mov_b32 m0, s39
	v_lshl_add_u64 v[184:185], v[220:221], 0, s[12:13]
	s_barrier
	ds_read_b128 v[144:147], v191 offset:49152
	ds_read_b128 v[148:151], v191 offset:50176
	ds_read_b128 v[168:171], v191 offset:51200
	ds_read_b128 v[172:175], v191 offset:52224
	ds_read_b128 v[176:179], v191 offset:53248
	ds_read_b128 v[180:183], v191 offset:54272
	ds_read_b128 v[194:197], v191 offset:55296
	ds_read_b128 v[198:201], v191 offset:56320
	global_load_lds_dwordx4 v[184:185], off
	v_lshl_add_u64 v[184:185], v[222:223], 0, s[12:13]
	s_mov_b32 m0, s40
	s_nop 0
	global_load_lds_dwordx4 v[184:185], off
	s_barrier
	s_waitcnt lgkmcnt(0)
	s_setprio 1
	s_waitcnt lgkmcnt(0)
	v_mfma_f32_16x16x32_bf16 v[60:63], v[128:131], v[144:147], v[60:63]
	v_mfma_f32_16x16x32_bf16 v[56:59], v[136:139], v[144:147], v[56:59]
	v_mfma_f32_16x16x32_bf16 v[44:47], v[128:131], v[168:171], v[44:47]
	v_mfma_f32_16x16x32_bf16 v[40:43], v[136:139], v[168:171], v[40:43]
	v_mfma_f32_16x16x32_bf16 v[28:31], v[128:131], v[176:179], v[28:31]
	v_mfma_f32_16x16x32_bf16 v[24:27], v[136:139], v[176:179], v[24:27]
	v_mfma_f32_16x16x32_bf16 v[12:15], v[128:131], v[194:197], v[12:15]
	v_mfma_f32_16x16x32_bf16 v[8:11], v[136:139], v[194:197], v[8:11]
	v_mfma_f32_16x16x32_bf16 v[60:63], v[132:135], v[148:151], v[60:63]
	v_mfma_f32_16x16x32_bf16 v[56:59], v[140:143], v[148:151], v[56:59]
	v_mfma_f32_16x16x32_bf16 v[44:47], v[132:135], v[172:175], v[44:47]
	v_mfma_f32_16x16x32_bf16 v[40:43], v[140:143], v[172:175], v[40:43]
	v_mfma_f32_16x16x32_bf16 v[28:31], v[132:135], v[180:183], v[28:31]
	v_mfma_f32_16x16x32_bf16 v[24:27], v[140:143], v[180:183], v[24:27]
	v_mfma_f32_16x16x32_bf16 v[12:15], v[132:135], v[198:201], v[12:15]
	v_mfma_f32_16x16x32_bf16 v[8:11], v[140:143], v[198:201], v[8:11]
	s_setprio 0
	s_barrier
	s_add_u32 s14, s20, 0xb0080
	s_addc_u32 s15, s21, 0
	s_add_i32 s20, s22, s31
	v_lshl_add_u64 v[128:129], s[14:15], 0, v[154:155]
	s_mov_b32 m0, s20
	s_nop 0
	global_load_lds_dwordx4 v[128:129], off
	v_lshl_add_u64 v[128:129], s[14:15], 0, v[158:159]
	s_add_i32 m0, s20, 0x2000
	s_nop 0
	global_load_lds_dwordx4 v[128:129], off
	s_waitcnt vmcnt(6)
	s_barrier
	s_setprio 1
	v_mfma_f32_16x16x32_bf16 v[52:55], v[202:205], v[144:147], v[52:55]
	v_mfma_f32_16x16x32_bf16 v[48:51], v[210:213], v[144:147], v[48:51]
	v_mfma_f32_16x16x32_bf16 v[36:39], v[202:205], v[168:171], v[36:39]
	v_mfma_f32_16x16x32_bf16 v[32:35], v[210:213], v[168:171], v[32:35]
	v_mfma_f32_16x16x32_bf16 v[20:23], v[202:205], v[176:179], v[20:23]
	v_mfma_f32_16x16x32_bf16 v[16:19], v[210:213], v[176:179], v[16:19]
	v_mfma_f32_16x16x32_bf16 v[4:7], v[202:205], v[194:197], v[4:7]
	v_mfma_f32_16x16x32_bf16 v[0:3], v[210:213], v[194:197], v[0:3]
	v_mfma_f32_16x16x32_bf16 v[52:55], v[206:209], v[148:151], v[52:55]
	v_mfma_f32_16x16x32_bf16 v[48:51], v[214:217], v[148:151], v[48:51]
	v_mfma_f32_16x16x32_bf16 v[36:39], v[206:209], v[172:175], v[36:39]
	v_mfma_f32_16x16x32_bf16 v[32:35], v[214:217], v[172:175], v[32:35]
	v_mfma_f32_16x16x32_bf16 v[20:23], v[206:209], v[180:183], v[20:23]
	v_mfma_f32_16x16x32_bf16 v[16:19], v[214:217], v[180:183], v[16:19]
	v_mfma_f32_16x16x32_bf16 v[4:7], v[206:209], v[198:201], v[4:7]
	v_mfma_f32_16x16x32_bf16 v[0:3], v[214:217], v[198:201], v[0:3]
	s_setprio 0
	s_add_i32 s51, s51, 2
	s_add_u32 s49, s49, 0x100
	s_addc_u32 s50, s50, 0
	s_cmp_gt_u32 s51, 41
	s_mov_b64 s[14:15], s[18:19]
	s_barrier
	s_cbranch_scc0 .LBB0_554
	v_lshl_or_b32 v168, s10, 8, v189
	v_lshl_add_u32 v170, s48, 8, v186
	v_ashrrev_i32_e32 v169, 31, v168
	v_lshlrev_b64 v[202:203], 1, v[168:169]
	v_ashrrev_i32_e32 v171, 31, v170
	v_or_b32_e32 v182, 16, v170
	v_lshl_add_u64 v[172:173], s[64:65], 0, v[202:203]
	v_lshlrev_b64 v[204:205], 11, v[170:171]
	v_ashrrev_i32_e32 v183, 31, v182
	v_or_b32_e32 v178, 32, v170
	v_lshl_add_u64 v[128:129], v[172:173], 0, v[204:205]
	v_lshlrev_b64 v[184:185], 11, v[182:183]
	v_ashrrev_i32_e32 v179, 31, v178
	v_or_b32_e32 v174, 48, v170
	global_load_dwordx4 v[194:197], v[128:129], off
	global_load_dwordx4 v[198:201], v[128:129], off offset:256
	v_lshl_add_u64 v[128:129], v[172:173], 0, v[184:185]
	v_lshlrev_b64 v[180:181], 11, v[178:179]
	v_ashrrev_i32_e32 v175, 31, v174
	global_load_dwordx4 v[148:151], v[128:129], off
	global_load_dwordx4 v[144:147], v[128:129], off offset:256
	v_lshl_add_u64 v[128:129], v[172:173], 0, v[180:181]
	v_lshlrev_b64 v[176:177], 11, v[174:175]
	global_load_dwordx4 v[140:143], v[128:129], off
	global_load_dwordx4 v[136:139], v[128:129], off offset:256
	v_lshl_add_u64 v[128:129], v[172:173], 0, v[176:177]
	global_load_dwordx4 v[132:135], v[128:129], off
	s_nop 0
	global_load_dwordx4 v[128:131], v[128:129], off offset:256
	s_lshl_b32 s14, s10, 2
	s_ashr_i32 s15, s14, 31
	v_add_u32_e32 v252, 0x80, v170
	v_ashrrev_i32_e32 v253, 31, v252
	v_lshlrev_b64 v[252:253], 11, v[252:253]
	v_lshl_add_u64 v[252:253], v[172:173], 0, v[252:253]
	global_load_dwordx4 v[236:239], v[252:253], off
	global_load_dwordx4 v[240:243], v[252:253], off offset:256
	v_add_u32_e32 v252, 0x90, v170
	v_ashrrev_i32_e32 v253, 31, v252
	v_lshlrev_b64 v[252:253], 11, v[252:253]
	v_lshl_add_u64 v[252:253], v[172:173], 0, v[252:253]
	global_load_dwordx4 v[244:247], v[252:253], off
	global_load_dwordx4 v[248:251], v[252:253], off offset:256
	v_add_u32_e32 v252, 0xa0, v170
	v_ashrrev_i32_e32 v253, 31, v252
	v_lshlrev_b64 v[252:253], 11, v[252:253]
	v_lshl_add_u64 v[252:253], v[172:173], 0, v[252:253]
	global_load_dwordx4 v[210:213], v[252:253], off
	global_load_dwordx4 v[214:217], v[252:253], off offset:256
	s_waitcnt vmcnt(6)
	v_lshlrev_b32_e32 v206, 16, v194
	v_and_b32_e32 v207, 0xffff0000, v194
	v_lshlrev_b32_e32 v194, 16, v195
	v_and_b32_e32 v195, 0xffff0000, v195
	v_lshlrev_b32_e32 v208, 16, v196
	v_and_b32_e32 v209, 0xffff0000, v196
	v_lshlrev_b32_e32 v196, 16, v197
	v_and_b32_e32 v197, 0xffff0000, v197
	v_pk_add_f32 v[126:127], v[126:127], v[194:195]
	v_pk_add_f32 v[124:125], v[124:125], v[206:207]
	v_pk_add_f32 v[194:195], v[122:123], v[196:197]
	v_pk_add_f32 v[122:123], v[120:121], v[208:209]
	v_mul_f32_e32 v120, v125, v125
	v_mul_f32_e32 v121, v127, v127
	v_fmac_f32_e32 v120, v124, v124
	v_fmac_f32_e32 v121, v126, v126
	v_add_f32_e32 v120, v120, v121
	v_mul_f32_e32 v121, v123, v123
	v_mul_f32_e32 v196, v195, v195
	v_fmac_f32_e32 v121, v122, v122
	v_fmac_f32_e32 v196, v194, v194
	v_add_f32_e32 v121, v121, v196
	v_add_f32_e32 v206, v120, v121
	v_cvt_pk_bf16_f32 v120, v124, v125
	v_cvt_pk_bf16_f32 v121, v126, v127
	v_lshlrev_b32_e32 v124, 16, v198
	v_and_b32_e32 v125, 0xffff0000, v198
	v_lshlrev_b32_e32 v126, 16, v199
	v_and_b32_e32 v127, 0xffff0000, v199
	v_cvt_pk_bf16_f32 v122, v122, v123
	v_cvt_pk_bf16_f32 v123, v194, v195
	v_lshlrev_b32_e32 v194, 16, v200
	v_and_b32_e32 v195, 0xffff0000, v200
	v_pk_add_f32 v[118:119], v[118:119], v[126:127]
	v_pk_add_f32 v[116:117], v[116:117], v[124:125]
	v_lshlrev_b32_e32 v196, 16, v201
	v_and_b32_e32 v197, 0xffff0000, v201
	v_pk_add_f32 v[126:127], v[112:113], v[194:195]
	v_mul_f32_e32 v112, v117, v117
	v_mul_f32_e32 v113, v119, v119
	v_pk_add_f32 v[124:125], v[114:115], v[196:197]
	v_fmac_f32_e32 v112, v116, v116
	v_fmac_f32_e32 v113, v118, v118
	v_add_f32_e32 v112, v112, v113
	v_mul_f32_e32 v113, v127, v127
	v_mul_f32_e32 v114, v125, v125
	v_fmac_f32_e32 v113, v126, v126
	v_fmac_f32_e32 v114, v124, v124
	v_add_f32_e32 v113, v113, v114
	v_add_f32_e32 v112, v112, v113
	v_and_b32_e32 v114, 64, v193
	v_add_f32_e32 v113, v206, v112
	v_xor_b32_e32 v112, 16, v193
	v_add_u32_e32 v196, 64, v114
	v_cmp_lt_i32_e32 vcc, v112, v196
	v_lshl_add_u64 v[114:115], s[64:65], 0, v[204:205]
	v_lshl_add_u64 v[194:195], v[114:115], 0, v[202:203]
	v_cndmask_b32_e32 v112, v193, v112, vcc
	v_lshlrev_b32_e32 v112, 2, v112
	ds_bpermute_b32 v197, v112, v113
	global_store_dwordx4 v[194:195], v[120:123], off
	v_cvt_pk_bf16_f32 v116, v116, v117
	v_cvt_pk_bf16_f32 v117, v118, v119
	v_cvt_pk_bf16_f32 v118, v126, v127
	s_waitcnt lgkmcnt(0)
	v_add_f32_e32 v114, v113, v197
	v_xor_b32_e32 v113, 32, v193
	v_cmp_lt_i32_e32 vcc, v113, v196
	v_cvt_pk_bf16_f32 v119, v124, v125
	global_store_dwordx4 v[194:195], v[116:119], off offset:256
	s_nop 0
	v_cndmask_b32_e32 v113, v193, v113, vcc
	v_lshlrev_b32_e32 v113, 2, v113
	ds_bpermute_b32 v115, v113, v114
	s_and_saveexec_b64 s[18:19], s[2:3]
	s_cbranch_execz .LBB0_557
	s_waitcnt lgkmcnt(0)
	v_add_f32_e32 v116, v114, v115
	v_lshlrev_b64 v[114:115], 6, v[170:171]
	v_lshl_add_u64 v[114:115], s[74:75], 0, v[114:115]
	v_lshl_add_u64 v[114:115], s[14:15], 2, v[114:115]
	s_lshl_b32 s10, s38, 2
	v_lshl_add_u64 v[114:115], v[114:115], 0, s[10:11]
	global_store_dword v[114:115], v116, off

.LBB0_563:
	s_or_b64 exec, exec, s[18:19]
	v_add_u32_e32 v100, 0x80, v170
	v_ashrrev_i32_e32 v101, 31, v100
	v_add_u32_e32 v96, 0x90, v170
	v_lshlrev_b64 v[110:111], 11, v[100:101]
	v_ashrrev_i32_e32 v97, 31, v96
	v_add_u32_e32 v92, 0xa0, v170
	s_waitcnt lgkmcnt(0)
	v_lshl_add_u64 v[64:65], v[172:173], 0, v[110:111]
	v_lshlrev_b64 v[98:99], 11, v[96:97]
	v_ashrrev_i32_e32 v93, 31, v92
	v_add_u32_e32 v88, 0xb0, v170
	v_lshl_add_u64 v[64:65], v[172:173], 0, v[98:99]
	v_lshlrev_b64 v[94:95], 11, v[92:93]
	v_ashrrev_i32_e32 v89, 31, v88
	v_lshl_add_u64 v[64:65], v[172:173], 0, v[94:95]
	v_lshlrev_b64 v[90:91], 11, v[88:89]
	v_lshl_add_u64 v[64:65], v[172:173], 0, v[90:91]
	global_load_dwordx4 v[68:71], v[64:65], off
	s_nop 0
	global_load_dwordx4 v[64:67], v[64:65], off offset:256
	s_waitcnt vmcnt(15)
	v_lshlrev_b32_e32 v114, 16, v236
	v_and_b32_e32 v115, 0xffff0000, v236
	v_lshlrev_b32_e32 v236, 16, v237
	v_and_b32_e32 v237, 0xffff0000, v237
	v_lshlrev_b32_e32 v116, 16, v238
	v_and_b32_e32 v117, 0xffff0000, v238
	v_lshlrev_b32_e32 v238, 16, v239
	v_and_b32_e32 v239, 0xffff0000, v239
	v_pk_add_f32 v[62:63], v[62:63], v[236:237]
	v_pk_add_f32 v[60:61], v[60:61], v[114:115]
	v_pk_add_f32 v[236:237], v[58:59], v[238:239]
	v_pk_add_f32 v[58:59], v[56:57], v[116:117]
	v_mul_f32_e32 v56, v61, v61
	v_mul_f32_e32 v57, v63, v63
	v_fmac_f32_e32 v56, v60, v60
	v_fmac_f32_e32 v57, v62, v62
	v_add_f32_e32 v56, v56, v57
	v_mul_f32_e32 v57, v59, v59
	v_mul_f32_e32 v238, v237, v237
	v_fmac_f32_e32 v57, v58, v58
	v_fmac_f32_e32 v238, v236, v236
	v_add_f32_e32 v57, v57, v238
	v_add_f32_e32 v114, v56, v57
	v_cvt_pk_bf16_f32 v56, v60, v61
	v_cvt_pk_bf16_f32 v57, v62, v63
	s_waitcnt vmcnt(14)
	v_lshlrev_b32_e32 v60, 16, v240
	v_and_b32_e32 v61, 0xffff0000, v240
	v_lshlrev_b32_e32 v62, 16, v241
	v_and_b32_e32 v63, 0xffff0000, v241
	v_cvt_pk_bf16_f32 v58, v58, v59
	v_cvt_pk_bf16_f32 v59, v236, v237
	v_lshlrev_b32_e32 v236, 16, v242
	v_and_b32_e32 v237, 0xffff0000, v242
	v_pk_add_f32 v[54:55], v[54:55], v[62:63]
	v_pk_add_f32 v[52:53], v[52:53], v[60:61]
	v_lshlrev_b32_e32 v238, 16, v243
	v_and_b32_e32 v239, 0xffff0000, v243
	v_pk_add_f32 v[62:63], v[48:49], v[236:237]
	v_mul_f32_e32 v48, v53, v53
	v_mul_f32_e32 v49, v55, v55
	v_pk_add_f32 v[60:61], v[50:51], v[238:239]
	v_fmac_f32_e32 v48, v52, v52
	v_fmac_f32_e32 v49, v54, v54
	v_add_f32_e32 v48, v48, v49
	v_mul_f32_e32 v49, v63, v63
	v_mul_f32_e32 v50, v61, v61
	v_fmac_f32_e32 v49, v62, v62
	v_fmac_f32_e32 v50, v60, v60
	v_add_f32_e32 v49, v49, v50
	v_add_f32_e32 v48, v48, v49
	v_add_f32_e32 v51, v114, v48
	ds_bpermute_b32 v238, v112, v51
	v_lshl_add_u64 v[48:49], s[64:65], 0, v[110:111]
	v_lshl_add_u64 v[236:237], v[168:169], 1, v[48:49]
	global_store_dwordx4 v[236:237], v[56:59], off
	v_cvt_pk_bf16_f32 v50, v52, v53
	s_waitcnt lgkmcnt(0)
	v_add_f32_e32 v48, v51, v238
	ds_bpermute_b32 v49, v113, v48
	v_cvt_pk_bf16_f32 v51, v54, v55
	v_cvt_pk_bf16_f32 v52, v62, v63
	v_cvt_pk_bf16_f32 v53, v60, v61
	global_store_dwordx4 v[236:237], v[50:53], off offset:256
	s_and_saveexec_b64 s[18:19], s[2:3]
	s_cbranch_execz .LBB0_565
	s_waitcnt lgkmcnt(0)
	v_add_f32_e32 v50, v48, v49
	v_lshlrev_b64 v[48:49], 6, v[100:101]
	v_lshl_add_u64 v[48:49], s[74:75], 0, v[48:49]
	v_lshl_add_u64 v[48:49], s[14:15], 2, v[48:49]
	s_lshl_b32 s10, s38, 2
	v_lshl_add_u64 v[48:49], v[48:49], 0, s[10:11]
	global_store_dword v[48:49], v50, off
.LBB0_565:
	s_or_b64 exec, exec, s[18:19]
	s_waitcnt vmcnt(15)
	v_lshlrev_b32_e32 v48, 16, v244
	s_waitcnt lgkmcnt(0)
	v_and_b32_e32 v49, 0xffff0000, v244
	v_lshlrev_b32_e32 v50, 16, v245
	v_and_b32_e32 v51, 0xffff0000, v245
	v_lshlrev_b32_e32 v52, 16, v246
	v_and_b32_e32 v53, 0xffff0000, v246
	v_lshlrev_b32_e32 v54, 16, v247
	v_and_b32_e32 v55, 0xffff0000, v247
	v_pk_add_f32 v[46:47], v[46:47], v[50:51]
	v_pk_add_f32 v[44:45], v[44:45], v[48:49]
	v_pk_add_f32 v[48:49], v[42:43], v[54:55]
	v_pk_add_f32 v[42:43], v[40:41], v[52:53]
	v_mul_f32_e32 v40, v45, v45
	v_mul_f32_e32 v41, v47, v47
	v_fmac_f32_e32 v40, v44, v44
	v_fmac_f32_e32 v41, v46, v46
	v_add_f32_e32 v40, v40, v41
	v_mul_f32_e32 v41, v43, v43
	v_mul_f32_e32 v50, v49, v49
	v_fmac_f32_e32 v41, v42, v42
	v_fmac_f32_e32 v50, v48, v48
	v_add_f32_e32 v41, v41, v50
	v_add_f32_e32 v52, v40, v41
	v_cvt_pk_bf16_f32 v40, v44, v45
	v_cvt_pk_bf16_f32 v41, v46, v47
	s_waitcnt vmcnt(14)
	v_lshlrev_b32_e32 v44, 16, v248
	v_and_b32_e32 v45, 0xffff0000, v248
	v_lshlrev_b32_e32 v46, 16, v249
	v_and_b32_e32 v47, 0xffff0000, v249
	v_cvt_pk_bf16_f32 v42, v42, v43
	v_cvt_pk_bf16_f32 v43, v48, v49
	v_lshlrev_b32_e32 v48, 16, v250
	v_and_b32_e32 v49, 0xffff0000, v250
	v_pk_add_f32 v[38:39], v[38:39], v[46:47]
	v_pk_add_f32 v[36:37], v[36:37], v[44:45]
	v_lshlrev_b32_e32 v50, 16, v251
	v_and_b32_e32 v51, 0xffff0000, v251
	v_pk_add_f32 v[46:47], v[32:33], v[48:49]
	v_mul_f32_e32 v32, v37, v37
	v_mul_f32_e32 v33, v39, v39
	v_pk_add_f32 v[44:45], v[34:35], v[50:51]
	v_fmac_f32_e32 v32, v36, v36
	v_fmac_f32_e32 v33, v38, v38
	v_add_f32_e32 v32, v32, v33
	v_mul_f32_e32 v33, v47, v47
	v_mul_f32_e32 v34, v45, v45
	v_fmac_f32_e32 v33, v46, v46
	v_fmac_f32_e32 v34, v44, v44
	v_add_f32_e32 v33, v33, v34
	v_add_f32_e32 v32, v32, v33
	v_add_f32_e32 v35, v52, v32
	ds_bpermute_b32 v50, v112, v35
	v_lshl_add_u64 v[32:33], s[64:65], 0, v[98:99]
	v_lshl_add_u64 v[48:49], v[168:169], 1, v[32:33]
	global_store_dwordx4 v[48:49], v[40:43], off
	v_cvt_pk_bf16_f32 v34, v36, v37
	s_waitcnt lgkmcnt(0)
	v_add_f32_e32 v32, v35, v50
	ds_bpermute_b32 v33, v113, v32
	v_cvt_pk_bf16_f32 v35, v38, v39
	v_cvt_pk_bf16_f32 v36, v46, v47
	v_cvt_pk_bf16_f32 v37, v44, v45
	global_store_dwordx4 v[48:49], v[34:37], off offset:256
	s_and_saveexec_b64 s[18:19], s[2:3]
	s_cbranch_execz .LBB0_567
	s_waitcnt lgkmcnt(0)
	v_add_f32_e32 v34, v32, v33
	v_lshlrev_b64 v[32:33], 6, v[96:97]
	v_lshl_add_u64 v[32:33], s[74:75], 0, v[32:33]
	v_lshl_add_u64 v[32:33], s[14:15], 2, v[32:33]
	s_lshl_b32 s10, s38, 2
	v_lshl_add_u64 v[32:33], v[32:33], 0, s[10:11]
	global_store_dword v[32:33], v34, off
.LBB0_567:
	s_or_b64 exec, exec, s[18:19]
	s_waitcnt vmcnt(15)
	v_lshlrev_b32_e32 v32, 16, v210
	s_waitcnt lgkmcnt(0)
	v_and_b32_e32 v33, 0xffff0000, v210
	v_lshlrev_b32_e32 v34, 16, v211
	v_and_b32_e32 v35, 0xffff0000, v211
	v_lshlrev_b32_e32 v36, 16, v212
	v_and_b32_e32 v37, 0xffff0000, v212
	v_lshlrev_b32_e32 v38, 16, v213
	v_and_b32_e32 v39, 0xffff0000, v213
	v_pk_add_f32 v[30:31], v[30:31], v[34:35]
	v_pk_add_f32 v[28:29], v[28:29], v[32:33]
	v_pk_add_f32 v[32:33], v[26:27], v[38:39]
	v_pk_add_f32 v[26:27], v[24:25], v[36:37]
	v_mul_f32_e32 v24, v29, v29
	v_mul_f32_e32 v25, v31, v31
	v_fmac_f32_e32 v24, v28, v28
	v_fmac_f32_e32 v25, v30, v30
	v_add_f32_e32 v24, v24, v25
	v_mul_f32_e32 v25, v27, v27
	v_mul_f32_e32 v34, v33, v33
	v_fmac_f32_e32 v25, v26, v26
	v_fmac_f32_e32 v34, v32, v32
	v_add_f32_e32 v25, v25, v34
	v_add_f32_e32 v36, v24, v25
	v_cvt_pk_bf16_f32 v24, v28, v29
	v_cvt_pk_bf16_f32 v25, v30, v31
	s_waitcnt vmcnt(14)
	v_lshlrev_b32_e32 v28, 16, v214
	v_and_b32_e32 v29, 0xffff0000, v214
	v_lshlrev_b32_e32 v30, 16, v215
	v_and_b32_e32 v31, 0xffff0000, v215
	v_cvt_pk_bf16_f32 v26, v26, v27
	v_cvt_pk_bf16_f32 v27, v32, v33
	v_lshlrev_b32_e32 v32, 16, v216
	v_and_b32_e32 v33, 0xffff0000, v216
	v_pk_add_f32 v[22:23], v[22:23], v[30:31]
	v_pk_add_f32 v[20:21], v[20:21], v[28:29]
	v_lshlrev_b32_e32 v34, 16, v217
	v_and_b32_e32 v35, 0xffff0000, v217
	v_pk_add_f32 v[30:31], v[16:17], v[32:33]
	v_mul_f32_e32 v16, v21, v21
	v_mul_f32_e32 v17, v23, v23
	v_pk_add_f32 v[28:29], v[18:19], v[34:35]
	v_fmac_f32_e32 v16, v20, v20
	v_fmac_f32_e32 v17, v22, v22
	v_add_f32_e32 v16, v16, v17
	v_mul_f32_e32 v17, v31, v31
	v_mul_f32_e32 v18, v29, v29
	v_fmac_f32_e32 v17, v30, v30
	v_fmac_f32_e32 v18, v28, v28
	v_add_f32_e32 v17, v17, v18
	v_add_f32_e32 v16, v16, v17
	v_add_f32_e32 v19, v36, v16
	ds_bpermute_b32 v34, v112, v19
	v_lshl_add_u64 v[16:17], s[64:65], 0, v[94:95]
	v_lshl_add_u64 v[32:33], v[168:169], 1, v[16:17]
	global_store_dwordx4 v[32:33], v[24:27], off
	v_cvt_pk_bf16_f32 v18, v20, v21
	s_waitcnt lgkmcnt(0)
	v_add_f32_e32 v16, v19, v34
	ds_bpermute_b32 v17, v113, v16
	v_cvt_pk_bf16_f32 v19, v22, v23
	v_cvt_pk_bf16_f32 v20, v30, v31
	v_cvt_pk_bf16_f32 v21, v28, v29
	global_store_dwordx4 v[32:33], v[18:21], off offset:256
	s_and_saveexec_b64 s[18:19], s[2:3]
	s_cbranch_execz .LBB0_569
	s_waitcnt lgkmcnt(0)
	v_add_f32_e32 v18, v16, v17
	v_lshlrev_b64 v[16:17], 6, v[92:93]
	v_lshl_add_u64 v[16:17], s[74:75], 0, v[16:17]
	v_lshl_add_u64 v[16:17], s[14:15], 2, v[16:17]
	s_lshl_b32 s10, s38, 2
	v_lshl_add_u64 v[16:17], v[16:17], 0, s[10:11]
	global_store_dword v[16:17], v18, off

.LBB0_1551:
	ds_read_b128 v[128:131], v190
	ds_read_b128 v[132:135], v190 offset:1024
	ds_read_b128 v[136:139], v190 offset:2048
	ds_read_b128 v[140:143], v190 offset:3072
	s_add_u32 s22, s20, 0xfffc0080
	s_addc_u32 s23, s21, -1
	s_cmp_eq_u32 s51, 12
	s_cselect_b32 s29, s13, s23
	s_cselect_b32 s28, s19, s22
	s_cselect_b32 s23, s11, s50
	s_cselect_b32 s22, s48, s49
	v_lshl_add_u64 v[184:185], s[20:21], 0, v[160:161]
	s_add_i32 m0, s36, 0xc000
	ds_read_b128 v[144:147], v191
	ds_read_b128 v[148:151], v191 offset:1024
	ds_read_b128 v[168:171], v191 offset:2048
	ds_read_b128 v[172:175], v191 offset:3072
	ds_read_b128 v[176:179], v191 offset:4096
	ds_read_b128 v[180:183], v191 offset:5120
	ds_read_b128 v[194:197], v191 offset:6144
	ds_read_b128 v[198:201], v191 offset:7168
	global_load_lds_dwordx4 v[184:185], off
	v_lshl_add_u64 v[184:185], s[20:21], 0, v[162:163]
	s_add_i32 m0, s36, 0xe000
	s_nop 0
	global_load_lds_dwordx4 v[184:185], off
	s_waitcnt lgkmcnt(8)
	s_barrier
	s_waitcnt lgkmcnt(0)
	s_setprio 1
	s_waitcnt lgkmcnt(0)
	v_mfma_f32_16x16x32_bf16 v[124:127], v[128:131], v[144:147], v[124:127]
	v_mfma_f32_16x16x32_bf16 v[120:123], v[136:139], v[144:147], v[120:123]
	v_mfma_f32_16x16x32_bf16 v[108:111], v[128:131], v[168:171], v[108:111]
	v_mfma_f32_16x16x32_bf16 v[104:107], v[136:139], v[168:171], v[104:107]
	v_mfma_f32_16x16x32_bf16 v[92:95], v[128:131], v[176:179], v[92:95]
	v_mfma_f32_16x16x32_bf16 v[88:91], v[136:139], v[176:179], v[88:91]
	v_mfma_f32_16x16x32_bf16 v[76:79], v[128:131], v[194:197], v[76:79]
	v_mfma_f32_16x16x32_bf16 v[72:75], v[136:139], v[194:197], v[72:75]
	v_mfma_f32_16x16x32_bf16 v[124:127], v[132:135], v[148:151], v[124:127]
	v_mfma_f32_16x16x32_bf16 v[120:123], v[140:143], v[148:151], v[120:123]
	v_mfma_f32_16x16x32_bf16 v[108:111], v[132:135], v[172:175], v[108:111]
	v_mfma_f32_16x16x32_bf16 v[104:107], v[140:143], v[172:175], v[104:107]
	v_mfma_f32_16x16x32_bf16 v[92:95], v[132:135], v[180:183], v[92:95]
	v_mfma_f32_16x16x32_bf16 v[88:91], v[140:143], v[180:183], v[88:91]
	v_mfma_f32_16x16x32_bf16 v[76:79], v[132:135], v[198:201], v[76:79]
	v_mfma_f32_16x16x32_bf16 v[72:75], v[140:143], v[198:201], v[72:75]
	s_setprio 0
	s_barrier
	s_add_i32 s52, s45, s35
	v_lshl_add_u64 v[184:185], s[22:23], 0, v[154:155]
	s_mov_b32 m0, s52
	ds_read_b128 v[202:205], v192
	ds_read_b128 v[206:209], v192 offset:1024
	ds_read_b128 v[210:213], v192 offset:2048
	ds_read_b128 v[214:217], v192 offset:3072
	global_load_lds_dwordx4 v[184:185], off
	v_lshl_add_u64 v[218:219], s[22:23], 0, v[158:159]
	s_add_i32 m0, s52, 0x2000
	s_nop 0
	global_load_lds_dwordx4 v[218:219], off
	s_barrier
	s_waitcnt lgkmcnt(0)
	s_setprio 1
	s_waitcnt lgkmcnt(0)
	v_mfma_f32_16x16x32_bf16 v[116:119], v[202:205], v[144:147], v[116:119]
	v_mfma_f32_16x16x32_bf16 v[112:115], v[210:213], v[144:147], v[112:115]
	v_mfma_f32_16x16x32_bf16 v[100:103], v[202:205], v[168:171], v[100:103]
	v_mfma_f32_16x16x32_bf16 v[96:99], v[210:213], v[168:171], v[96:99]
	v_mfma_f32_16x16x32_bf16 v[84:87], v[202:205], v[176:179], v[84:87]
	v_mfma_f32_16x16x32_bf16 v[80:83], v[210:213], v[176:179], v[80:83]
	v_mfma_f32_16x16x32_bf16 v[68:71], v[202:205], v[194:197], v[68:71]
	v_mfma_f32_16x16x32_bf16 v[64:67], v[210:213], v[194:197], v[64:67]
	v_mfma_f32_16x16x32_bf16 v[116:119], v[206:209], v[148:151], v[116:119]
	v_mfma_f32_16x16x32_bf16 v[112:115], v[214:217], v[148:151], v[112:115]
	v_mfma_f32_16x16x32_bf16 v[100:103], v[206:209], v[172:175], v[100:103]
	v_mfma_f32_16x16x32_bf16 v[96:99], v[214:217], v[172:175], v[96:99]
	v_mfma_f32_16x16x32_bf16 v[84:87], v[206:209], v[180:183], v[84:87]
	v_mfma_f32_16x16x32_bf16 v[80:83], v[214:217], v[180:183], v[80:83]
	v_mfma_f32_16x16x32_bf16 v[68:71], v[206:209], v[198:201], v[68:71]
	v_mfma_f32_16x16x32_bf16 v[64:67], v[214:217], v[198:201], v[64:67]
	s_setprio 0
	s_mov_b32 m0, s36
	v_lshl_add_u64 v[220:221], s[28:29], 0, v[152:153]
	s_barrier
	ds_read_b128 v[144:147], v191 offset:16384
	ds_read_b128 v[148:151], v191 offset:17408
	ds_read_b128 v[168:171], v191 offset:18432
	ds_read_b128 v[172:175], v191 offset:19456
	ds_read_b128 v[176:179], v191 offset:20480
	ds_read_b128 v[180:183], v191 offset:21504
	ds_read_b128 v[194:197], v191 offset:22528
	ds_read_b128 v[198:201], v191 offset:23552
	global_load_lds_dwordx4 v[220:221], off
	v_lshl_add_u64 v[222:223], s[28:29], 0, v[156:157]
	s_mov_b32 m0, s37
	s_nop 0
	global_load_lds_dwordx4 v[222:223], off
	s_barrier
	s_waitcnt lgkmcnt(0)
	s_setprio 1
	s_waitcnt lgkmcnt(0)
	v_mfma_f32_16x16x32_bf16 v[60:63], v[128:131], v[144:147], v[60:63]
	v_mfma_f32_16x16x32_bf16 v[56:59], v[136:139], v[144:147], v[56:59]
	v_mfma_f32_16x16x32_bf16 v[44:47], v[128:131], v[168:171], v[44:47]
	v_mfma_f32_16x16x32_bf16 v[40:43], v[136:139], v[168:171], v[40:43]
	v_mfma_f32_16x16x32_bf16 v[28:31], v[128:131], v[176:179], v[28:31]
	v_mfma_f32_16x16x32_bf16 v[24:27], v[136:139], v[176:179], v[24:27]
	v_mfma_f32_16x16x32_bf16 v[12:15], v[128:131], v[194:197], v[12:15]
	v_mfma_f32_16x16x32_bf16 v[8:11], v[136:139], v[194:197], v[8:11]
	v_mfma_f32_16x16x32_bf16 v[60:63], v[132:135], v[148:151], v[60:63]
	v_mfma_f32_16x16x32_bf16 v[56:59], v[140:143], v[148:151], v[56:59]
	v_mfma_f32_16x16x32_bf16 v[44:47], v[132:135], v[172:175], v[44:47]
	v_mfma_f32_16x16x32_bf16 v[40:43], v[140:143], v[172:175], v[40:43]
	v_mfma_f32_16x16x32_bf16 v[28:31], v[132:135], v[180:183], v[28:31]
	v_mfma_f32_16x16x32_bf16 v[24:27], v[140:143], v[180:183], v[24:27]
	v_mfma_f32_16x16x32_bf16 v[12:15], v[132:135], v[198:201], v[12:15]
	v_mfma_f32_16x16x32_bf16 v[8:11], v[140:143], v[198:201], v[8:11]
	s_setprio 0
	s_barrier
	s_add_u32 s52, s22, 0x40000
	s_addc_u32 s53, s23, 0
	s_add_i32 s54, s46, s35
	v_lshl_add_u64 v[128:129], s[52:53], 0, v[154:155]
	s_mov_b32 m0, s54
	s_nop 0
	global_load_lds_dwordx4 v[128:129], off
	v_lshl_add_u64 v[128:129], s[52:53], 0, v[158:159]
	s_add_i32 m0, s54, 0x2000
	s_nop 0
	global_load_lds_dwordx4 v[128:129], off
	s_waitcnt vmcnt(6)
	s_barrier
	s_setprio 1
	v_mfma_f32_16x16x32_bf16 v[52:55], v[202:205], v[144:147], v[52:55]
	v_mfma_f32_16x16x32_bf16 v[48:51], v[210:213], v[144:147], v[48:51]
	v_mfma_f32_16x16x32_bf16 v[36:39], v[202:205], v[168:171], v[36:39]
	v_mfma_f32_16x16x32_bf16 v[32:35], v[210:213], v[168:171], v[32:35]
	v_mfma_f32_16x16x32_bf16 v[20:23], v[202:205], v[176:179], v[20:23]
	v_mfma_f32_16x16x32_bf16 v[16:19], v[210:213], v[176:179], v[16:19]
	v_mfma_f32_16x16x32_bf16 v[4:7], v[202:205], v[194:197], v[4:7]
	v_mfma_f32_16x16x32_bf16 v[0:3], v[210:213], v[194:197], v[0:3]
	v_mfma_f32_16x16x32_bf16 v[52:55], v[206:209], v[148:151], v[52:55]
	v_mfma_f32_16x16x32_bf16 v[48:51], v[214:217], v[148:151], v[48:51]
	v_mfma_f32_16x16x32_bf16 v[36:39], v[206:209], v[172:175], v[36:39]
	v_mfma_f32_16x16x32_bf16 v[32:35], v[214:217], v[172:175], v[32:35]
	v_mfma_f32_16x16x32_bf16 v[20:23], v[206:209], v[180:183], v[20:23]
	v_mfma_f32_16x16x32_bf16 v[16:19], v[214:217], v[180:183], v[16:19]
	v_mfma_f32_16x16x32_bf16 v[4:7], v[206:209], v[198:201], v[4:7]
	v_mfma_f32_16x16x32_bf16 v[0:3], v[214:217], v[198:201], v[0:3]
	s_setprio 0
	s_add_i32 s52, 0, 0x18000
	v_add_u32_e32 v140, s52, v187
	s_barrier
	ds_read_b128 v[128:131], v140
	ds_read_b128 v[132:135], v140 offset:1024
	ds_read_b128 v[136:139], v140 offset:2048
	ds_read_b128 v[140:143], v140 offset:3072
	s_add_u32 s28, s28, 0x40000
	s_addc_u32 s29, s29, 0
	s_mov_b32 m0, s38
	v_lshl_add_u64 v[202:203], s[28:29], 0, v[152:153]
	ds_read_b128 v[144:147], v191 offset:32768
	ds_read_b128 v[148:151], v191 offset:33792
	ds_read_b128 v[168:171], v191 offset:34816
	ds_read_b128 v[172:175], v191 offset:35840
	ds_read_b128 v[176:179], v191 offset:36864
	ds_read_b128 v[180:183], v191 offset:37888
	ds_read_b128 v[194:197], v191 offset:38912
	ds_read_b128 v[198:201], v191 offset:39936
	global_load_lds_dwordx4 v[202:203], off
	v_lshl_add_u64 v[202:203], s[28:29], 0, v[156:157]
	s_mov_b32 m0, s39
	s_nop 0
	global_load_lds_dwordx4 v[202:203], off
	s_waitcnt lgkmcnt(8)
	s_barrier
	s_waitcnt lgkmcnt(0)
	s_setprio 1
	s_waitcnt lgkmcnt(0)
	v_mfma_f32_16x16x32_bf16 v[124:127], v[128:131], v[144:147], v[124:127]
	v_mfma_f32_16x16x32_bf16 v[120:123], v[136:139], v[144:147], v[120:123]
	v_mfma_f32_16x16x32_bf16 v[108:111], v[128:131], v[168:171], v[108:111]
	v_mfma_f32_16x16x32_bf16 v[104:107], v[136:139], v[168:171], v[104:107]
	v_mfma_f32_16x16x32_bf16 v[92:95], v[128:131], v[176:179], v[92:95]
	v_mfma_f32_16x16x32_bf16 v[88:91], v[136:139], v[176:179], v[88:91]
	v_mfma_f32_16x16x32_bf16 v[76:79], v[128:131], v[194:197], v[76:79]
	v_mfma_f32_16x16x32_bf16 v[72:75], v[136:139], v[194:197], v[72:75]
	v_mfma_f32_16x16x32_bf16 v[124:127], v[132:135], v[148:151], v[124:127]
	v_mfma_f32_16x16x32_bf16 v[120:123], v[140:143], v[148:151], v[120:123]
	v_mfma_f32_16x16x32_bf16 v[108:111], v[132:135], v[172:175], v[108:111]
	v_mfma_f32_16x16x32_bf16 v[104:107], v[140:143], v[172:175], v[104:107]
	v_mfma_f32_16x16x32_bf16 v[92:95], v[132:135], v[180:183], v[92:95]
	v_mfma_f32_16x16x32_bf16 v[88:91], v[140:143], v[180:183], v[88:91]
	v_mfma_f32_16x16x32_bf16 v[76:79], v[132:135], v[198:201], v[76:79]
	v_mfma_f32_16x16x32_bf16 v[72:75], v[140:143], v[198:201], v[72:75]
	s_setprio 0
	s_barrier
	s_add_i32 s28, 0, 0x1c000
	s_add_i32 s29, s52, s35
	v_add_u32_e32 v214, s28, v187
	v_lshl_add_u64 v[184:185], v[184:185], 0, s[8:9]
	s_mov_b32 m0, s29
	ds_read_b128 v[202:205], v214
	ds_read_b128 v[206:209], v214 offset:1024
	ds_read_b128 v[210:213], v214 offset:2048
	ds_read_b128 v[214:217], v214 offset:3072
	global_load_lds_dwordx4 v[184:185], off
	v_lshl_add_u64 v[184:185], v[218:219], 0, s[8:9]
	s_add_i32 m0, s29, 0x2000
	s_nop 0
	global_load_lds_dwordx4 v[184:185], off
	s_barrier
	s_waitcnt lgkmcnt(0)
	s_setprio 1
	s_waitcnt lgkmcnt(0)
	v_mfma_f32_16x16x32_bf16 v[116:119], v[202:205], v[144:147], v[116:119]
	v_mfma_f32_16x16x32_bf16 v[112:115], v[210:213], v[144:147], v[112:115]
	v_mfma_f32_16x16x32_bf16 v[100:103], v[202:205], v[168:171], v[100:103]
	v_mfma_f32_16x16x32_bf16 v[96:99], v[210:213], v[168:171], v[96:99]
	v_mfma_f32_16x16x32_bf16 v[84:87], v[202:205], v[176:179], v[84:87]
	v_mfma_f32_16x16x32_bf16 v[80:83], v[210:213], v[176:179], v[80:83]
	v_mfma_f32_16x16x32_bf16 v[68:71], v[202:205], v[194:197], v[68:71]
	v_mfma_f32_16x16x32_bf16 v[64:67], v[210:213], v[194:197], v[64:67]
	v_mfma_f32_16x16x32_bf16 v[116:119], v[206:209], v[148:151], v[116:119]
	v_mfma_f32_16x16x32_bf16 v[112:115], v[214:217], v[148:151], v[112:115]
	v_mfma_f32_16x16x32_bf16 v[100:103], v[206:209], v[172:175], v[100:103]
	v_mfma_f32_16x16x32_bf16 v[96:99], v[214:217], v[172:175], v[96:99]
	v_mfma_f32_16x16x32_bf16 v[84:87], v[206:209], v[180:183], v[84:87]
	v_mfma_f32_16x16x32_bf16 v[80:83], v[214:217], v[180:183], v[80:83]
	v_mfma_f32_16x16x32_bf16 v[68:71], v[206:209], v[198:201], v[68:71]
	v_mfma_f32_16x16x32_bf16 v[64:67], v[214:217], v[198:201], v[64:67]
	s_setprio 0
	s_mov_b32 m0, s41
	v_lshl_add_u64 v[184:185], v[220:221], 0, s[8:9]
	s_barrier
	ds_read_b128 v[144:147], v191 offset:49152
	ds_read_b128 v[148:151], v191 offset:50176
	ds_read_b128 v[168:171], v191 offset:51200
	ds_read_b128 v[172:175], v191 offset:52224
	ds_read_b128 v[176:179], v191 offset:53248
	ds_read_b128 v[180:183], v191 offset:54272
	ds_read_b128 v[194:197], v191 offset:55296
	ds_read_b128 v[198:201], v191 offset:56320
	global_load_lds_dwordx4 v[184:185], off
	v_lshl_add_u64 v[184:185], v[222:223], 0, s[8:9]
	s_mov_b32 m0, s42
	s_nop 0
	global_load_lds_dwordx4 v[184:185], off
	s_barrier
	s_waitcnt lgkmcnt(0)
	s_setprio 1
	s_waitcnt lgkmcnt(0)
	v_mfma_f32_16x16x32_bf16 v[60:63], v[128:131], v[144:147], v[60:63]
	v_mfma_f32_16x16x32_bf16 v[56:59], v[136:139], v[144:147], v[56:59]
	v_mfma_f32_16x16x32_bf16 v[44:47], v[128:131], v[168:171], v[44:47]
	v_mfma_f32_16x16x32_bf16 v[40:43], v[136:139], v[168:171], v[40:43]
	v_mfma_f32_16x16x32_bf16 v[28:31], v[128:131], v[176:179], v[28:31]
	v_mfma_f32_16x16x32_bf16 v[24:27], v[136:139], v[176:179], v[24:27]
	v_mfma_f32_16x16x32_bf16 v[12:15], v[128:131], v[194:197], v[12:15]
	v_mfma_f32_16x16x32_bf16 v[8:11], v[136:139], v[194:197], v[8:11]
	v_mfma_f32_16x16x32_bf16 v[60:63], v[132:135], v[148:151], v[60:63]
	v_mfma_f32_16x16x32_bf16 v[56:59], v[140:143], v[148:151], v[56:59]
	v_mfma_f32_16x16x32_bf16 v[44:47], v[132:135], v[172:175], v[44:47]
	v_mfma_f32_16x16x32_bf16 v[40:43], v[140:143], v[172:175], v[40:43]
	v_mfma_f32_16x16x32_bf16 v[28:31], v[132:135], v[180:183], v[28:31]
	v_mfma_f32_16x16x32_bf16 v[24:27], v[140:143], v[180:183], v[24:27]
	v_mfma_f32_16x16x32_bf16 v[12:15], v[132:135], v[198:201], v[12:15]
	v_mfma_f32_16x16x32_bf16 v[8:11], v[140:143], v[198:201], v[8:11]
	s_setprio 0
	s_barrier
	s_add_u32 s22, s22, 0x40080
	s_addc_u32 s23, s23, 0
	s_add_i32 s28, s28, s35
	v_lshl_add_u64 v[128:129], s[22:23], 0, v[154:155]
	s_mov_b32 m0, s28
	s_nop 0
	global_load_lds_dwordx4 v[128:129], off
	v_lshl_add_u64 v[128:129], s[22:23], 0, v[158:159]
	s_add_i32 m0, s28, 0x2000
	s_nop 0
	global_load_lds_dwordx4 v[128:129], off
	s_waitcnt vmcnt(6)
	s_barrier
	s_setprio 1
	v_mfma_f32_16x16x32_bf16 v[52:55], v[202:205], v[144:147], v[52:55]
	v_mfma_f32_16x16x32_bf16 v[48:51], v[210:213], v[144:147], v[48:51]
	v_mfma_f32_16x16x32_bf16 v[36:39], v[202:205], v[168:171], v[36:39]
	v_mfma_f32_16x16x32_bf16 v[32:35], v[210:213], v[168:171], v[32:35]
	v_mfma_f32_16x16x32_bf16 v[20:23], v[202:205], v[176:179], v[20:23]
	v_mfma_f32_16x16x32_bf16 v[16:19], v[210:213], v[176:179], v[16:19]
	v_mfma_f32_16x16x32_bf16 v[4:7], v[202:205], v[194:197], v[4:7]
	v_mfma_f32_16x16x32_bf16 v[0:3], v[210:213], v[194:197], v[0:3]
	v_mfma_f32_16x16x32_bf16 v[52:55], v[206:209], v[148:151], v[52:55]
	v_mfma_f32_16x16x32_bf16 v[48:51], v[214:217], v[148:151], v[48:51]
	v_mfma_f32_16x16x32_bf16 v[36:39], v[206:209], v[172:175], v[36:39]
	v_mfma_f32_16x16x32_bf16 v[32:35], v[214:217], v[172:175], v[32:35]
	v_mfma_f32_16x16x32_bf16 v[20:23], v[206:209], v[180:183], v[20:23]
	v_mfma_f32_16x16x32_bf16 v[16:19], v[214:217], v[180:183], v[16:19]
	v_mfma_f32_16x16x32_bf16 v[4:7], v[206:209], v[198:201], v[4:7]
	v_mfma_f32_16x16x32_bf16 v[0:3], v[214:217], v[198:201], v[0:3]
	s_setprio 0
	s_add_i32 s51, s51, 2
	s_add_u32 s20, s20, 0x100
	s_addc_u32 s21, s21, 0
	s_add_u32 s49, s49, 0x100
	s_addc_u32 s50, s50, 0
	s_cmp_gt_u32 s51, 13
	s_barrier
	s_cbranch_scc0 .LBB0_1551
	v_lshl_or_b32 v168, s6, 8, v189
	v_lshl_add_u32 v170, s18, 8, v186
	v_ashrrev_i32_e32 v169, 31, v168
	v_lshlrev_b64 v[202:203], 1, v[168:169]
	v_ashrrev_i32_e32 v171, 31, v170
	v_or_b32_e32 v182, 16, v170
	v_lshl_add_u64 v[172:173], s[64:65], 0, v[202:203]
	v_lshlrev_b64 v[204:205], 11, v[170:171]
	v_ashrrev_i32_e32 v183, 31, v182
	v_or_b32_e32 v178, 32, v170
	v_lshl_add_u64 v[128:129], v[172:173], 0, v[204:205]
	v_lshlrev_b64 v[184:185], 11, v[182:183]
	v_ashrrev_i32_e32 v179, 31, v178
	v_or_b32_e32 v174, 48, v170
	global_load_dwordx4 v[194:197], v[128:129], off
	global_load_dwordx4 v[198:201], v[128:129], off offset:256
	v_lshl_add_u64 v[128:129], v[172:173], 0, v[184:185]
	v_lshlrev_b64 v[180:181], 11, v[178:179]
	v_ashrrev_i32_e32 v175, 31, v174
	global_load_dwordx4 v[148:151], v[128:129], off
	global_load_dwordx4 v[144:147], v[128:129], off offset:256
	v_lshl_add_u64 v[128:129], v[172:173], 0, v[180:181]
	v_lshlrev_b64 v[176:177], 11, v[174:175]
	global_load_dwordx4 v[140:143], v[128:129], off
	global_load_dwordx4 v[136:139], v[128:129], off offset:256
	v_lshl_add_u64 v[128:129], v[172:173], 0, v[176:177]
	global_load_dwordx4 v[132:135], v[128:129], off
	s_nop 0
	global_load_dwordx4 v[128:131], v[128:129], off offset:256
	s_lshl_b32 s18, s6, 2
	s_ashr_i32 s19, s18, 31
	v_add_u32_e32 v252, 0x80, v170
	v_ashrrev_i32_e32 v253, 31, v252
	v_lshlrev_b64 v[252:253], 11, v[252:253]
	v_lshl_add_u64 v[252:253], v[172:173], 0, v[252:253]
	global_load_dwordx4 v[236:239], v[252:253], off
	global_load_dwordx4 v[240:243], v[252:253], off offset:256
	v_add_u32_e32 v252, 0x90, v170
	v_ashrrev_i32_e32 v253, 31, v252
	v_lshlrev_b64 v[252:253], 11, v[252:253]
	v_lshl_add_u64 v[252:253], v[172:173], 0, v[252:253]
	global_load_dwordx4 v[244:247], v[252:253], off
	global_load_dwordx4 v[248:251], v[252:253], off offset:256
	v_add_u32_e32 v252, 0xa0, v170
	v_ashrrev_i32_e32 v253, 31, v252
	v_lshlrev_b64 v[252:253], 11, v[252:253]
	v_lshl_add_u64 v[252:253], v[172:173], 0, v[252:253]
	global_load_dwordx4 v[210:213], v[252:253], off
	global_load_dwordx4 v[214:217], v[252:253], off offset:256
	s_waitcnt vmcnt(6)
	v_lshlrev_b32_e32 v206, 16, v194
	v_and_b32_e32 v207, 0xffff0000, v194
	v_lshlrev_b32_e32 v194, 16, v195
	v_and_b32_e32 v195, 0xffff0000, v195
	v_lshlrev_b32_e32 v208, 16, v196
	v_and_b32_e32 v209, 0xffff0000, v196
	v_lshlrev_b32_e32 v196, 16, v197
	v_and_b32_e32 v197, 0xffff0000, v197
	v_pk_add_f32 v[126:127], v[126:127], v[194:195]
	v_pk_add_f32 v[124:125], v[124:125], v[206:207]
	v_pk_add_f32 v[194:195], v[122:123], v[196:197]
	v_pk_add_f32 v[122:123], v[120:121], v[208:209]
	v_mul_f32_e32 v120, v125, v125
	v_mul_f32_e32 v121, v127, v127
	v_fmac_f32_e32 v120, v124, v124
	v_fmac_f32_e32 v121, v126, v126
	v_add_f32_e32 v120, v120, v121
	v_mul_f32_e32 v121, v123, v123
	v_mul_f32_e32 v196, v195, v195
	v_fmac_f32_e32 v121, v122, v122
	v_fmac_f32_e32 v196, v194, v194
	v_add_f32_e32 v121, v121, v196
	v_add_f32_e32 v206, v120, v121
	v_cvt_pk_bf16_f32 v120, v124, v125
	v_cvt_pk_bf16_f32 v121, v126, v127
	v_lshlrev_b32_e32 v124, 16, v198
	v_and_b32_e32 v125, 0xffff0000, v198
	v_lshlrev_b32_e32 v126, 16, v199
	v_and_b32_e32 v127, 0xffff0000, v199
	v_cvt_pk_bf16_f32 v122, v122, v123
	v_cvt_pk_bf16_f32 v123, v194, v195
	v_lshlrev_b32_e32 v194, 16, v200
	v_and_b32_e32 v195, 0xffff0000, v200
	v_pk_add_f32 v[118:119], v[118:119], v[126:127]
	v_pk_add_f32 v[116:117], v[116:117], v[124:125]
	v_lshlrev_b32_e32 v196, 16, v201
	v_and_b32_e32 v197, 0xffff0000, v201
	v_pk_add_f32 v[126:127], v[112:113], v[194:195]
	v_mul_f32_e32 v112, v117, v117
	v_mul_f32_e32 v113, v119, v119
	v_pk_add_f32 v[124:125], v[114:115], v[196:197]
	v_fmac_f32_e32 v112, v116, v116
	v_fmac_f32_e32 v113, v118, v118
	v_add_f32_e32 v112, v112, v113
	v_mul_f32_e32 v113, v127, v127
	v_mul_f32_e32 v114, v125, v125
	v_fmac_f32_e32 v113, v126, v126
	v_fmac_f32_e32 v114, v124, v124
	v_add_f32_e32 v113, v113, v114
	v_add_f32_e32 v112, v112, v113
	v_and_b32_e32 v114, 64, v193
	v_add_f32_e32 v113, v206, v112
	v_xor_b32_e32 v112, 16, v193
	v_add_u32_e32 v196, 64, v114
	v_cmp_lt_i32_e32 vcc, v112, v196
	v_lshl_add_u64 v[114:115], s[64:65], 0, v[204:205]
	v_lshl_add_u64 v[194:195], v[114:115], 0, v[202:203]
	v_cndmask_b32_e32 v112, v193, v112, vcc
	v_lshlrev_b32_e32 v112, 2, v112
	ds_bpermute_b32 v197, v112, v113
	global_store_dwordx4 v[194:195], v[120:123], off
	v_cvt_pk_bf16_f32 v116, v116, v117
	v_cvt_pk_bf16_f32 v117, v118, v119
	v_cvt_pk_bf16_f32 v118, v126, v127
	s_waitcnt lgkmcnt(0)
	v_add_f32_e32 v114, v113, v197
	v_xor_b32_e32 v113, 32, v193
	v_cmp_lt_i32_e32 vcc, v113, v196
	v_cvt_pk_bf16_f32 v119, v124, v125
	global_store_dwordx4 v[194:195], v[116:119], off offset:256
	s_nop 0
	v_cndmask_b32_e32 v113, v193, v113, vcc
	v_lshlrev_b32_e32 v113, 2, v113
	ds_bpermute_b32 v115, v113, v114
	s_and_saveexec_b64 s[20:21], s[2:3]
	s_cbranch_execz .LBB0_1554
	s_waitcnt lgkmcnt(0)
	v_add_f32_e32 v116, v114, v115
	v_lshlrev_b64 v[114:115], 6, v[170:171]
	v_lshl_add_u64 v[114:115], s[74:75], 0, v[114:115]
	v_lshl_add_u64 v[114:115], s[18:19], 2, v[114:115]
	s_lshl_b32 s6, s40, 2
	v_lshl_add_u64 v[114:115], v[114:115], 0, s[6:7]
	global_store_dword v[114:115], v116, off

.LBB0_1560:
	s_or_b64 exec, exec, s[20:21]
	v_add_u32_e32 v100, 0x80, v170
	v_ashrrev_i32_e32 v101, 31, v100
	v_add_u32_e32 v96, 0x90, v170
	v_lshlrev_b64 v[110:111], 11, v[100:101]
	v_ashrrev_i32_e32 v97, 31, v96
	v_add_u32_e32 v92, 0xa0, v170
	s_waitcnt lgkmcnt(0)
	v_lshl_add_u64 v[64:65], v[172:173], 0, v[110:111]
	v_lshlrev_b64 v[98:99], 11, v[96:97]
	v_ashrrev_i32_e32 v93, 31, v92
	v_add_u32_e32 v88, 0xb0, v170
	v_lshl_add_u64 v[64:65], v[172:173], 0, v[98:99]
	v_lshlrev_b64 v[94:95], 11, v[92:93]
	v_ashrrev_i32_e32 v89, 31, v88
	v_lshl_add_u64 v[64:65], v[172:173], 0, v[94:95]
	v_lshlrev_b64 v[90:91], 11, v[88:89]
	v_lshl_add_u64 v[64:65], v[172:173], 0, v[90:91]
	global_load_dwordx4 v[68:71], v[64:65], off
	s_nop 0
	global_load_dwordx4 v[64:67], v[64:65], off offset:256
	s_waitcnt vmcnt(15)
	v_lshlrev_b32_e32 v114, 16, v236
	v_and_b32_e32 v115, 0xffff0000, v236
	v_lshlrev_b32_e32 v236, 16, v237
	v_and_b32_e32 v237, 0xffff0000, v237
	v_lshlrev_b32_e32 v116, 16, v238
	v_and_b32_e32 v117, 0xffff0000, v238
	v_lshlrev_b32_e32 v238, 16, v239
	v_and_b32_e32 v239, 0xffff0000, v239
	v_pk_add_f32 v[62:63], v[62:63], v[236:237]
	v_pk_add_f32 v[60:61], v[60:61], v[114:115]
	v_pk_add_f32 v[236:237], v[58:59], v[238:239]
	v_pk_add_f32 v[58:59], v[56:57], v[116:117]
	v_mul_f32_e32 v56, v61, v61
	v_mul_f32_e32 v57, v63, v63
	v_fmac_f32_e32 v56, v60, v60
	v_fmac_f32_e32 v57, v62, v62
	v_add_f32_e32 v56, v56, v57
	v_mul_f32_e32 v57, v59, v59
	v_mul_f32_e32 v238, v237, v237
	v_fmac_f32_e32 v57, v58, v58
	v_fmac_f32_e32 v238, v236, v236
	v_add_f32_e32 v57, v57, v238
	v_add_f32_e32 v114, v56, v57
	v_cvt_pk_bf16_f32 v56, v60, v61
	v_cvt_pk_bf16_f32 v57, v62, v63
	s_waitcnt vmcnt(14)
	v_lshlrev_b32_e32 v60, 16, v240
	v_and_b32_e32 v61, 0xffff0000, v240
	v_lshlrev_b32_e32 v62, 16, v241
	v_and_b32_e32 v63, 0xffff0000, v241
	v_cvt_pk_bf16_f32 v58, v58, v59
	v_cvt_pk_bf16_f32 v59, v236, v237
	v_lshlrev_b32_e32 v236, 16, v242
	v_and_b32_e32 v237, 0xffff0000, v242
	v_pk_add_f32 v[54:55], v[54:55], v[62:63]
	v_pk_add_f32 v[52:53], v[52:53], v[60:61]
	v_lshlrev_b32_e32 v238, 16, v243
	v_and_b32_e32 v239, 0xffff0000, v243
	v_pk_add_f32 v[62:63], v[48:49], v[236:237]
	v_mul_f32_e32 v48, v53, v53
	v_mul_f32_e32 v49, v55, v55
	v_pk_add_f32 v[60:61], v[50:51], v[238:239]
	v_fmac_f32_e32 v48, v52, v52
	v_fmac_f32_e32 v49, v54, v54
	v_add_f32_e32 v48, v48, v49
	v_mul_f32_e32 v49, v63, v63
	v_mul_f32_e32 v50, v61, v61
	v_fmac_f32_e32 v49, v62, v62
	v_fmac_f32_e32 v50, v60, v60
	v_add_f32_e32 v49, v49, v50
	v_add_f32_e32 v48, v48, v49
	v_add_f32_e32 v51, v114, v48
	ds_bpermute_b32 v238, v112, v51
	v_lshl_add_u64 v[48:49], s[64:65], 0, v[110:111]
	v_lshl_add_u64 v[236:237], v[168:169], 1, v[48:49]
	global_store_dwordx4 v[236:237], v[56:59], off
	v_cvt_pk_bf16_f32 v50, v52, v53
	s_waitcnt lgkmcnt(0)
	v_add_f32_e32 v48, v51, v238
	ds_bpermute_b32 v49, v113, v48
	v_cvt_pk_bf16_f32 v51, v54, v55
	v_cvt_pk_bf16_f32 v52, v62, v63
	v_cvt_pk_bf16_f32 v53, v60, v61
	global_store_dwordx4 v[236:237], v[50:53], off offset:256
	s_and_saveexec_b64 s[20:21], s[2:3]
	s_cbranch_execz .LBB0_1562
	s_waitcnt lgkmcnt(0)
	v_add_f32_e32 v50, v48, v49
	v_lshlrev_b64 v[48:49], 6, v[100:101]
	v_lshl_add_u64 v[48:49], s[74:75], 0, v[48:49]
	v_lshl_add_u64 v[48:49], s[18:19], 2, v[48:49]
	s_lshl_b32 s6, s40, 2
	v_lshl_add_u64 v[48:49], v[48:49], 0, s[6:7]
	global_store_dword v[48:49], v50, off
.LBB0_1562:
	s_or_b64 exec, exec, s[20:21]
	s_waitcnt vmcnt(15)
	v_lshlrev_b32_e32 v48, 16, v244
	s_waitcnt lgkmcnt(0)
	v_and_b32_e32 v49, 0xffff0000, v244
	v_lshlrev_b32_e32 v50, 16, v245
	v_and_b32_e32 v51, 0xffff0000, v245
	v_lshlrev_b32_e32 v52, 16, v246
	v_and_b32_e32 v53, 0xffff0000, v246
	v_lshlrev_b32_e32 v54, 16, v247
	v_and_b32_e32 v55, 0xffff0000, v247
	v_pk_add_f32 v[46:47], v[46:47], v[50:51]
	v_pk_add_f32 v[44:45], v[44:45], v[48:49]
	v_pk_add_f32 v[48:49], v[42:43], v[54:55]
	v_pk_add_f32 v[42:43], v[40:41], v[52:53]
	v_mul_f32_e32 v40, v45, v45
	v_mul_f32_e32 v41, v47, v47
	v_fmac_f32_e32 v40, v44, v44
	v_fmac_f32_e32 v41, v46, v46
	v_add_f32_e32 v40, v40, v41
	v_mul_f32_e32 v41, v43, v43
	v_mul_f32_e32 v50, v49, v49
	v_fmac_f32_e32 v41, v42, v42
	v_fmac_f32_e32 v50, v48, v48
	v_add_f32_e32 v41, v41, v50
	v_add_f32_e32 v52, v40, v41
	v_cvt_pk_bf16_f32 v40, v44, v45
	v_cvt_pk_bf16_f32 v41, v46, v47
	s_waitcnt vmcnt(14)
	v_lshlrev_b32_e32 v44, 16, v248
	v_and_b32_e32 v45, 0xffff0000, v248
	v_lshlrev_b32_e32 v46, 16, v249
	v_and_b32_e32 v47, 0xffff0000, v249
	v_cvt_pk_bf16_f32 v42, v42, v43
	v_cvt_pk_bf16_f32 v43, v48, v49
	v_lshlrev_b32_e32 v48, 16, v250
	v_and_b32_e32 v49, 0xffff0000, v250
	v_pk_add_f32 v[38:39], v[38:39], v[46:47]
	v_pk_add_f32 v[36:37], v[36:37], v[44:45]
	v_lshlrev_b32_e32 v50, 16, v251
	v_and_b32_e32 v51, 0xffff0000, v251
	v_pk_add_f32 v[46:47], v[32:33], v[48:49]
	v_mul_f32_e32 v32, v37, v37
	v_mul_f32_e32 v33, v39, v39
	v_pk_add_f32 v[44:45], v[34:35], v[50:51]
	v_fmac_f32_e32 v32, v36, v36
	v_fmac_f32_e32 v33, v38, v38
	v_add_f32_e32 v32, v32, v33
	v_mul_f32_e32 v33, v47, v47
	v_mul_f32_e32 v34, v45, v45
	v_fmac_f32_e32 v33, v46, v46
	v_fmac_f32_e32 v34, v44, v44
	v_add_f32_e32 v33, v33, v34
	v_add_f32_e32 v32, v32, v33
	v_add_f32_e32 v35, v52, v32
	ds_bpermute_b32 v50, v112, v35
	v_lshl_add_u64 v[32:33], s[64:65], 0, v[98:99]
	v_lshl_add_u64 v[48:49], v[168:169], 1, v[32:33]
	global_store_dwordx4 v[48:49], v[40:43], off
	v_cvt_pk_bf16_f32 v34, v36, v37
	s_waitcnt lgkmcnt(0)
	v_add_f32_e32 v32, v35, v50
	ds_bpermute_b32 v33, v113, v32
	v_cvt_pk_bf16_f32 v35, v38, v39
	v_cvt_pk_bf16_f32 v36, v46, v47
	v_cvt_pk_bf16_f32 v37, v44, v45
	global_store_dwordx4 v[48:49], v[34:37], off offset:256
	s_and_saveexec_b64 s[20:21], s[2:3]
	s_cbranch_execz .LBB0_1564
	s_waitcnt lgkmcnt(0)
	v_add_f32_e32 v34, v32, v33
	v_lshlrev_b64 v[32:33], 6, v[96:97]
	v_lshl_add_u64 v[32:33], s[74:75], 0, v[32:33]
	v_lshl_add_u64 v[32:33], s[18:19], 2, v[32:33]
	s_lshl_b32 s6, s40, 2
	v_lshl_add_u64 v[32:33], v[32:33], 0, s[6:7]
	global_store_dword v[32:33], v34, off
.LBB0_1564:
	s_or_b64 exec, exec, s[20:21]
	s_waitcnt vmcnt(15)
	v_lshlrev_b32_e32 v32, 16, v210
	s_waitcnt lgkmcnt(0)
	v_and_b32_e32 v33, 0xffff0000, v210
	v_lshlrev_b32_e32 v34, 16, v211
	v_and_b32_e32 v35, 0xffff0000, v211
	v_lshlrev_b32_e32 v36, 16, v212
	v_and_b32_e32 v37, 0xffff0000, v212
	v_lshlrev_b32_e32 v38, 16, v213
	v_and_b32_e32 v39, 0xffff0000, v213
	v_pk_add_f32 v[30:31], v[30:31], v[34:35]
	v_pk_add_f32 v[28:29], v[28:29], v[32:33]
	v_pk_add_f32 v[32:33], v[26:27], v[38:39]
	v_pk_add_f32 v[26:27], v[24:25], v[36:37]
	v_mul_f32_e32 v24, v29, v29
	v_mul_f32_e32 v25, v31, v31
	v_fmac_f32_e32 v24, v28, v28
	v_fmac_f32_e32 v25, v30, v30
	v_add_f32_e32 v24, v24, v25
	v_mul_f32_e32 v25, v27, v27
	v_mul_f32_e32 v34, v33, v33
	v_fmac_f32_e32 v25, v26, v26
	v_fmac_f32_e32 v34, v32, v32
	v_add_f32_e32 v25, v25, v34
	v_add_f32_e32 v36, v24, v25
	v_cvt_pk_bf16_f32 v24, v28, v29
	v_cvt_pk_bf16_f32 v25, v30, v31
	s_waitcnt vmcnt(14)
	v_lshlrev_b32_e32 v28, 16, v214
	v_and_b32_e32 v29, 0xffff0000, v214
	v_lshlrev_b32_e32 v30, 16, v215
	v_and_b32_e32 v31, 0xffff0000, v215
	v_cvt_pk_bf16_f32 v26, v26, v27
	v_cvt_pk_bf16_f32 v27, v32, v33
	v_lshlrev_b32_e32 v32, 16, v216
	v_and_b32_e32 v33, 0xffff0000, v216
	v_pk_add_f32 v[22:23], v[22:23], v[30:31]
	v_pk_add_f32 v[20:21], v[20:21], v[28:29]
	v_lshlrev_b32_e32 v34, 16, v217
	v_and_b32_e32 v35, 0xffff0000, v217
	v_pk_add_f32 v[30:31], v[16:17], v[32:33]
	v_mul_f32_e32 v16, v21, v21
	v_mul_f32_e32 v17, v23, v23
	v_pk_add_f32 v[28:29], v[18:19], v[34:35]
	v_fmac_f32_e32 v16, v20, v20
	v_fmac_f32_e32 v17, v22, v22
	v_add_f32_e32 v16, v16, v17
	v_mul_f32_e32 v17, v31, v31
	v_mul_f32_e32 v18, v29, v29
	v_fmac_f32_e32 v17, v30, v30
	v_fmac_f32_e32 v18, v28, v28
	v_add_f32_e32 v17, v17, v18
	v_add_f32_e32 v16, v16, v17
	v_add_f32_e32 v19, v36, v16
	ds_bpermute_b32 v34, v112, v19
	v_lshl_add_u64 v[16:17], s[64:65], 0, v[94:95]
	v_lshl_add_u64 v[32:33], v[168:169], 1, v[16:17]
	global_store_dwordx4 v[32:33], v[24:27], off
	v_cvt_pk_bf16_f32 v18, v20, v21
	s_waitcnt lgkmcnt(0)
	v_add_f32_e32 v16, v19, v34
	ds_bpermute_b32 v17, v113, v16
	v_cvt_pk_bf16_f32 v19, v22, v23
	v_cvt_pk_bf16_f32 v20, v30, v31
	v_cvt_pk_bf16_f32 v21, v28, v29
	global_store_dwordx4 v[32:33], v[18:21], off offset:256
	s_and_saveexec_b64 s[20:21], s[2:3]
	s_cbranch_execz .LBB0_1566
	s_waitcnt lgkmcnt(0)
	v_add_f32_e32 v18, v16, v17
	v_lshlrev_b64 v[16:17], 6, v[92:93]
	v_lshl_add_u64 v[16:17], s[74:75], 0, v[16:17]
	v_lshl_add_u64 v[16:17], s[18:19], 2, v[16:17]
	s_lshl_b32 s6, s40, 2
	v_lshl_add_u64 v[16:17], v[16:17], 0, s[6:7]
	global_store_dword v[16:17], v18, off

.LBB0_1741:
	ds_read_b128 v[128:131], v190
	ds_read_b128 v[132:135], v190 offset:1024
	ds_read_b128 v[136:139], v190 offset:2048
	ds_read_b128 v[140:143], v190 offset:3072
	s_add_u32 s16, s14, 0x100
	s_addc_u32 s17, s15, 0
	s_cmp_eq_u32 s47, 40
	s_cselect_b32 s21, s1, s17
	s_cselect_b32 s20, s0, s16
	s_cselect_b32 s19, s7, s46
	s_cselect_b32 s18, s6, s45
	v_lshl_add_u64 v[184:185], s[14:15], 0, v[160:161]
	s_add_i32 m0, s28, 0xc000
	ds_read_b128 v[144:147], v191
	ds_read_b128 v[148:151], v191 offset:1024
	ds_read_b128 v[168:171], v191 offset:2048
	ds_read_b128 v[172:175], v191 offset:3072
	ds_read_b128 v[176:179], v191 offset:4096
	ds_read_b128 v[180:183], v191 offset:5120
	ds_read_b128 v[194:197], v191 offset:6144
	ds_read_b128 v[198:201], v191 offset:7168
	global_load_lds_dwordx4 v[184:185], off
	v_lshl_add_u64 v[184:185], s[14:15], 0, v[162:163]
	s_add_i32 m0, s28, 0xe000
	s_nop 0
	global_load_lds_dwordx4 v[184:185], off
	s_waitcnt lgkmcnt(8)
	s_barrier
	s_waitcnt lgkmcnt(0)
	s_setprio 1
	s_waitcnt lgkmcnt(0)
	v_mfma_f32_16x16x32_bf16 v[124:127], v[128:131], v[144:147], v[124:127]
	v_mfma_f32_16x16x32_bf16 v[120:123], v[136:139], v[144:147], v[120:123]
	v_mfma_f32_16x16x32_bf16 v[108:111], v[128:131], v[168:171], v[108:111]
	v_mfma_f32_16x16x32_bf16 v[104:107], v[136:139], v[168:171], v[104:107]
	v_mfma_f32_16x16x32_bf16 v[92:95], v[128:131], v[176:179], v[92:95]
	v_mfma_f32_16x16x32_bf16 v[88:91], v[136:139], v[176:179], v[88:91]
	v_mfma_f32_16x16x32_bf16 v[76:79], v[128:131], v[194:197], v[76:79]
	v_mfma_f32_16x16x32_bf16 v[72:75], v[136:139], v[194:197], v[72:75]
	v_mfma_f32_16x16x32_bf16 v[124:127], v[132:135], v[148:151], v[124:127]
	v_mfma_f32_16x16x32_bf16 v[120:123], v[140:143], v[148:151], v[120:123]
	v_mfma_f32_16x16x32_bf16 v[108:111], v[132:135], v[172:175], v[108:111]
	v_mfma_f32_16x16x32_bf16 v[104:107], v[140:143], v[172:175], v[104:107]
	v_mfma_f32_16x16x32_bf16 v[92:95], v[132:135], v[180:183], v[92:95]
	v_mfma_f32_16x16x32_bf16 v[88:91], v[140:143], v[180:183], v[88:91]
	v_mfma_f32_16x16x32_bf16 v[76:79], v[132:135], v[198:201], v[76:79]
	v_mfma_f32_16x16x32_bf16 v[72:75], v[140:143], v[198:201], v[72:75]
	s_setprio 0
	s_barrier
	s_add_i32 s14, s39, s27
	v_lshl_add_u64 v[184:185], s[18:19], 0, v[154:155]
	s_mov_b32 m0, s14
	ds_read_b128 v[202:205], v192
	ds_read_b128 v[206:209], v192 offset:1024
	ds_read_b128 v[210:213], v192 offset:2048
	ds_read_b128 v[214:217], v192 offset:3072
	global_load_lds_dwordx4 v[184:185], off
	v_lshl_add_u64 v[218:219], s[18:19], 0, v[158:159]
	s_add_i32 m0, s14, 0x2000
	s_nop 0
	global_load_lds_dwordx4 v[218:219], off
	s_barrier
	s_waitcnt lgkmcnt(0)
	s_setprio 1
	s_waitcnt lgkmcnt(0)
	v_mfma_f32_16x16x32_bf16 v[116:119], v[202:205], v[144:147], v[116:119]
	v_mfma_f32_16x16x32_bf16 v[112:115], v[210:213], v[144:147], v[112:115]
	v_mfma_f32_16x16x32_bf16 v[100:103], v[202:205], v[168:171], v[100:103]
	v_mfma_f32_16x16x32_bf16 v[96:99], v[210:213], v[168:171], v[96:99]
	v_mfma_f32_16x16x32_bf16 v[84:87], v[202:205], v[176:179], v[84:87]
	v_mfma_f32_16x16x32_bf16 v[80:83], v[210:213], v[176:179], v[80:83]
	v_mfma_f32_16x16x32_bf16 v[68:71], v[202:205], v[194:197], v[68:71]
	v_mfma_f32_16x16x32_bf16 v[64:67], v[210:213], v[194:197], v[64:67]
	v_mfma_f32_16x16x32_bf16 v[116:119], v[206:209], v[148:151], v[116:119]
	v_mfma_f32_16x16x32_bf16 v[112:115], v[214:217], v[148:151], v[112:115]
	v_mfma_f32_16x16x32_bf16 v[100:103], v[206:209], v[172:175], v[100:103]
	v_mfma_f32_16x16x32_bf16 v[96:99], v[214:217], v[172:175], v[96:99]
	v_mfma_f32_16x16x32_bf16 v[84:87], v[206:209], v[180:183], v[84:87]
	v_mfma_f32_16x16x32_bf16 v[80:83], v[214:217], v[180:183], v[80:83]
	v_mfma_f32_16x16x32_bf16 v[68:71], v[206:209], v[198:201], v[68:71]
	v_mfma_f32_16x16x32_bf16 v[64:67], v[214:217], v[198:201], v[64:67]
	s_setprio 0
	s_mov_b32 m0, s28
	v_lshl_add_u64 v[220:221], s[20:21], 0, v[152:153]
	s_barrier
	ds_read_b128 v[144:147], v191 offset:16384
	ds_read_b128 v[148:151], v191 offset:17408
	ds_read_b128 v[168:171], v191 offset:18432
	ds_read_b128 v[172:175], v191 offset:19456
	ds_read_b128 v[176:179], v191 offset:20480
	ds_read_b128 v[180:183], v191 offset:21504
	ds_read_b128 v[194:197], v191 offset:22528
	ds_read_b128 v[198:201], v191 offset:23552
	global_load_lds_dwordx4 v[220:221], off
	v_lshl_add_u64 v[222:223], s[20:21], 0, v[156:157]
	s_mov_b32 m0, s29
	s_nop 0
	global_load_lds_dwordx4 v[222:223], off
	s_barrier
	s_waitcnt lgkmcnt(0)
	s_setprio 1
	s_waitcnt lgkmcnt(0)
	v_mfma_f32_16x16x32_bf16 v[60:63], v[128:131], v[144:147], v[60:63]
	v_mfma_f32_16x16x32_bf16 v[56:59], v[136:139], v[144:147], v[56:59]
	v_mfma_f32_16x16x32_bf16 v[44:47], v[128:131], v[168:171], v[44:47]
	v_mfma_f32_16x16x32_bf16 v[40:43], v[136:139], v[168:171], v[40:43]
	v_mfma_f32_16x16x32_bf16 v[28:31], v[128:131], v[176:179], v[28:31]
	v_mfma_f32_16x16x32_bf16 v[24:27], v[136:139], v[176:179], v[24:27]
	v_mfma_f32_16x16x32_bf16 v[12:15], v[128:131], v[194:197], v[12:15]
	v_mfma_f32_16x16x32_bf16 v[8:11], v[136:139], v[194:197], v[8:11]
	v_mfma_f32_16x16x32_bf16 v[60:63], v[132:135], v[148:151], v[60:63]
	v_mfma_f32_16x16x32_bf16 v[56:59], v[140:143], v[148:151], v[56:59]
	v_mfma_f32_16x16x32_bf16 v[44:47], v[132:135], v[172:175], v[44:47]
	v_mfma_f32_16x16x32_bf16 v[40:43], v[140:143], v[172:175], v[40:43]
	v_mfma_f32_16x16x32_bf16 v[28:31], v[132:135], v[180:183], v[28:31]
	v_mfma_f32_16x16x32_bf16 v[24:27], v[140:143], v[180:183], v[24:27]
	v_mfma_f32_16x16x32_bf16 v[12:15], v[132:135], v[198:201], v[12:15]
	v_mfma_f32_16x16x32_bf16 v[8:11], v[140:143], v[198:201], v[8:11]
	s_setprio 0
	s_barrier
	s_add_u32 s14, s18, 0xb0000
	s_addc_u32 s15, s19, 0
	s_add_i32 s48, s40, s27
	v_lshl_add_u64 v[128:129], s[14:15], 0, v[154:155]
	s_mov_b32 m0, s48
	s_nop 0
	global_load_lds_dwordx4 v[128:129], off
	v_lshl_add_u64 v[128:129], s[14:15], 0, v[158:159]
	s_add_i32 m0, s48, 0x2000
	s_nop 0
	global_load_lds_dwordx4 v[128:129], off
	s_waitcnt vmcnt(6)
	s_barrier
	s_setprio 1
	v_mfma_f32_16x16x32_bf16 v[52:55], v[202:205], v[144:147], v[52:55]
	v_mfma_f32_16x16x32_bf16 v[48:51], v[210:213], v[144:147], v[48:51]
	v_mfma_f32_16x16x32_bf16 v[36:39], v[202:205], v[168:171], v[36:39]
	v_mfma_f32_16x16x32_bf16 v[32:35], v[210:213], v[168:171], v[32:35]
	v_mfma_f32_16x16x32_bf16 v[20:23], v[202:205], v[176:179], v[20:23]
	v_mfma_f32_16x16x32_bf16 v[16:19], v[210:213], v[176:179], v[16:19]
	v_mfma_f32_16x16x32_bf16 v[4:7], v[202:205], v[194:197], v[4:7]
	v_mfma_f32_16x16x32_bf16 v[0:3], v[210:213], v[194:197], v[0:3]
	v_mfma_f32_16x16x32_bf16 v[52:55], v[206:209], v[148:151], v[52:55]
	v_mfma_f32_16x16x32_bf16 v[48:51], v[214:217], v[148:151], v[48:51]
	v_mfma_f32_16x16x32_bf16 v[36:39], v[206:209], v[172:175], v[36:39]
	v_mfma_f32_16x16x32_bf16 v[32:35], v[214:217], v[172:175], v[32:35]
	v_mfma_f32_16x16x32_bf16 v[20:23], v[206:209], v[180:183], v[20:23]
	v_mfma_f32_16x16x32_bf16 v[16:19], v[214:217], v[180:183], v[16:19]
	v_mfma_f32_16x16x32_bf16 v[4:7], v[206:209], v[198:201], v[4:7]
	v_mfma_f32_16x16x32_bf16 v[0:3], v[214:217], v[198:201], v[0:3]
	s_setprio 0
	s_add_i32 s48, 0, 0x18000
	v_add_u32_e32 v140, s48, v187
	s_barrier
	ds_read_b128 v[128:131], v140
	ds_read_b128 v[132:135], v140 offset:1024
	ds_read_b128 v[136:139], v140 offset:2048
	ds_read_b128 v[140:143], v140 offset:3072
	s_add_u32 s14, s20, 0xb0000
	s_addc_u32 s15, s21, 0
	s_mov_b32 m0, s30
	v_lshl_add_u64 v[202:203], s[14:15], 0, v[152:153]
	ds_read_b128 v[144:147], v191 offset:32768
	ds_read_b128 v[148:151], v191 offset:33792
	ds_read_b128 v[168:171], v191 offset:34816
	ds_read_b128 v[172:175], v191 offset:35840
	ds_read_b128 v[176:179], v191 offset:36864
	ds_read_b128 v[180:183], v191 offset:37888
	ds_read_b128 v[194:197], v191 offset:38912
	ds_read_b128 v[198:201], v191 offset:39936
	global_load_lds_dwordx4 v[202:203], off
	v_lshl_add_u64 v[202:203], s[14:15], 0, v[156:157]
	s_mov_b32 m0, s31
	s_nop 0
	global_load_lds_dwordx4 v[202:203], off
	s_waitcnt lgkmcnt(8)
	s_barrier
	s_waitcnt lgkmcnt(0)
	s_setprio 1
	s_waitcnt lgkmcnt(0)
	v_mfma_f32_16x16x32_bf16 v[124:127], v[128:131], v[144:147], v[124:127]
	v_mfma_f32_16x16x32_bf16 v[120:123], v[136:139], v[144:147], v[120:123]
	v_mfma_f32_16x16x32_bf16 v[108:111], v[128:131], v[168:171], v[108:111]
	v_mfma_f32_16x16x32_bf16 v[104:107], v[136:139], v[168:171], v[104:107]
	v_mfma_f32_16x16x32_bf16 v[92:95], v[128:131], v[176:179], v[92:95]
	v_mfma_f32_16x16x32_bf16 v[88:91], v[136:139], v[176:179], v[88:91]
	v_mfma_f32_16x16x32_bf16 v[76:79], v[128:131], v[194:197], v[76:79]
	v_mfma_f32_16x16x32_bf16 v[72:75], v[136:139], v[194:197], v[72:75]
	v_mfma_f32_16x16x32_bf16 v[124:127], v[132:135], v[148:151], v[124:127]
	v_mfma_f32_16x16x32_bf16 v[120:123], v[140:143], v[148:151], v[120:123]
	v_mfma_f32_16x16x32_bf16 v[108:111], v[132:135], v[172:175], v[108:111]
	v_mfma_f32_16x16x32_bf16 v[104:107], v[140:143], v[172:175], v[104:107]
	v_mfma_f32_16x16x32_bf16 v[92:95], v[132:135], v[180:183], v[92:95]
	v_mfma_f32_16x16x32_bf16 v[88:91], v[140:143], v[180:183], v[88:91]
	v_mfma_f32_16x16x32_bf16 v[76:79], v[132:135], v[198:201], v[76:79]
	v_mfma_f32_16x16x32_bf16 v[72:75], v[140:143], v[198:201], v[72:75]
	s_setprio 0
	s_barrier
	s_add_i32 s20, 0, 0x1c000
	s_add_i32 s14, s48, s27
	v_add_u32_e32 v214, s20, v187
	v_lshl_add_u64 v[184:185], v[184:185], 0, s[12:13]
	s_mov_b32 m0, s14
	ds_read_b128 v[202:205], v214
	ds_read_b128 v[206:209], v214 offset:1024
	ds_read_b128 v[210:213], v214 offset:2048
	ds_read_b128 v[214:217], v214 offset:3072
	global_load_lds_dwordx4 v[184:185], off
	v_lshl_add_u64 v[184:185], v[218:219], 0, s[12:13]
	s_add_i32 m0, s14, 0x2000
	s_nop 0
	global_load_lds_dwordx4 v[184:185], off
	s_barrier
	s_waitcnt lgkmcnt(0)
	s_setprio 1
	s_waitcnt lgkmcnt(0)
	v_mfma_f32_16x16x32_bf16 v[116:119], v[202:205], v[144:147], v[116:119]
	v_mfma_f32_16x16x32_bf16 v[112:115], v[210:213], v[144:147], v[112:115]
	v_mfma_f32_16x16x32_bf16 v[100:103], v[202:205], v[168:171], v[100:103]
	v_mfma_f32_16x16x32_bf16 v[96:99], v[210:213], v[168:171], v[96:99]
	v_mfma_f32_16x16x32_bf16 v[84:87], v[202:205], v[176:179], v[84:87]
	v_mfma_f32_16x16x32_bf16 v[80:83], v[210:213], v[176:179], v[80:83]
	v_mfma_f32_16x16x32_bf16 v[68:71], v[202:205], v[194:197], v[68:71]
	v_mfma_f32_16x16x32_bf16 v[64:67], v[210:213], v[194:197], v[64:67]
	v_mfma_f32_16x16x32_bf16 v[116:119], v[206:209], v[148:151], v[116:119]
	v_mfma_f32_16x16x32_bf16 v[112:115], v[214:217], v[148:151], v[112:115]
	v_mfma_f32_16x16x32_bf16 v[100:103], v[206:209], v[172:175], v[100:103]
	v_mfma_f32_16x16x32_bf16 v[96:99], v[214:217], v[172:175], v[96:99]
	v_mfma_f32_16x16x32_bf16 v[84:87], v[206:209], v[180:183], v[84:87]
	v_mfma_f32_16x16x32_bf16 v[80:83], v[214:217], v[180:183], v[80:83]
	v_mfma_f32_16x16x32_bf16 v[68:71], v[206:209], v[198:201], v[68:71]
	v_mfma_f32_16x16x32_bf16 v[64:67], v[214:217], v[198:201], v[64:67]
	s_setprio 0
	s_mov_b32 m0, s35
	v_lshl_add_u64 v[184:185], v[220:221], 0, s[12:13]
	s_barrier
	ds_read_b128 v[144:147], v191 offset:49152
	ds_read_b128 v[148:151], v191 offset:50176
	ds_read_b128 v[168:171], v191 offset:51200
	ds_read_b128 v[172:175], v191 offset:52224
	ds_read_b128 v[176:179], v191 offset:53248
	ds_read_b128 v[180:183], v191 offset:54272
	ds_read_b128 v[194:197], v191 offset:55296
	ds_read_b128 v[198:201], v191 offset:56320
	global_load_lds_dwordx4 v[184:185], off
	v_lshl_add_u64 v[184:185], v[222:223], 0, s[12:13]
	s_mov_b32 m0, s36
	s_nop 0
	global_load_lds_dwordx4 v[184:185], off
	s_barrier
	s_waitcnt lgkmcnt(0)
	s_setprio 1
	s_waitcnt lgkmcnt(0)
	v_mfma_f32_16x16x32_bf16 v[60:63], v[128:131], v[144:147], v[60:63]
	v_mfma_f32_16x16x32_bf16 v[56:59], v[136:139], v[144:147], v[56:59]
	v_mfma_f32_16x16x32_bf16 v[44:47], v[128:131], v[168:171], v[44:47]
	v_mfma_f32_16x16x32_bf16 v[40:43], v[136:139], v[168:171], v[40:43]
	v_mfma_f32_16x16x32_bf16 v[28:31], v[128:131], v[176:179], v[28:31]
	v_mfma_f32_16x16x32_bf16 v[24:27], v[136:139], v[176:179], v[24:27]
	v_mfma_f32_16x16x32_bf16 v[12:15], v[128:131], v[194:197], v[12:15]
	v_mfma_f32_16x16x32_bf16 v[8:11], v[136:139], v[194:197], v[8:11]
	v_mfma_f32_16x16x32_bf16 v[60:63], v[132:135], v[148:151], v[60:63]
	v_mfma_f32_16x16x32_bf16 v[56:59], v[140:143], v[148:151], v[56:59]
	v_mfma_f32_16x16x32_bf16 v[44:47], v[132:135], v[172:175], v[44:47]
	v_mfma_f32_16x16x32_bf16 v[40:43], v[140:143], v[172:175], v[40:43]
	v_mfma_f32_16x16x32_bf16 v[28:31], v[132:135], v[180:183], v[28:31]
	v_mfma_f32_16x16x32_bf16 v[24:27], v[140:143], v[180:183], v[24:27]
	v_mfma_f32_16x16x32_bf16 v[12:15], v[132:135], v[198:201], v[12:15]
	v_mfma_f32_16x16x32_bf16 v[8:11], v[140:143], v[198:201], v[8:11]
	s_setprio 0
	s_barrier
	s_add_u32 s14, s18, 0xb0080
	s_addc_u32 s15, s19, 0
	s_add_i32 s18, s20, s27
	v_lshl_add_u64 v[128:129], s[14:15], 0, v[154:155]
	s_mov_b32 m0, s18
	s_nop 0
	global_load_lds_dwordx4 v[128:129], off
	v_lshl_add_u64 v[128:129], s[14:15], 0, v[158:159]
	s_add_i32 m0, s18, 0x2000
	s_nop 0
	global_load_lds_dwordx4 v[128:129], off
	s_waitcnt vmcnt(6)
	s_barrier
	s_setprio 1
	v_mfma_f32_16x16x32_bf16 v[52:55], v[202:205], v[144:147], v[52:55]
	v_mfma_f32_16x16x32_bf16 v[48:51], v[210:213], v[144:147], v[48:51]
	v_mfma_f32_16x16x32_bf16 v[36:39], v[202:205], v[168:171], v[36:39]
	v_mfma_f32_16x16x32_bf16 v[32:35], v[210:213], v[168:171], v[32:35]
	v_mfma_f32_16x16x32_bf16 v[20:23], v[202:205], v[176:179], v[20:23]
	v_mfma_f32_16x16x32_bf16 v[16:19], v[210:213], v[176:179], v[16:19]
	v_mfma_f32_16x16x32_bf16 v[4:7], v[202:205], v[194:197], v[4:7]
	v_mfma_f32_16x16x32_bf16 v[0:3], v[210:213], v[194:197], v[0:3]
	v_mfma_f32_16x16x32_bf16 v[52:55], v[206:209], v[148:151], v[52:55]
	v_mfma_f32_16x16x32_bf16 v[48:51], v[214:217], v[148:151], v[48:51]
	v_mfma_f32_16x16x32_bf16 v[36:39], v[206:209], v[172:175], v[36:39]
	v_mfma_f32_16x16x32_bf16 v[32:35], v[214:217], v[172:175], v[32:35]
	v_mfma_f32_16x16x32_bf16 v[20:23], v[206:209], v[180:183], v[20:23]
	v_mfma_f32_16x16x32_bf16 v[16:19], v[214:217], v[180:183], v[16:19]
	v_mfma_f32_16x16x32_bf16 v[4:7], v[206:209], v[198:201], v[4:7]
	v_mfma_f32_16x16x32_bf16 v[0:3], v[214:217], v[198:201], v[0:3]
	s_setprio 0
	s_add_i32 s47, s47, 2
	s_add_u32 s45, s45, 0x100
	s_addc_u32 s46, s46, 0
	s_cmp_gt_u32 s47, 41
	s_mov_b64 s[14:15], s[16:17]
	s_barrier
	s_cbranch_scc0 .LBB0_1741
	v_lshl_or_b32 v168, s10, 8, v189
	v_lshl_add_u32 v170, s44, 8, v186
	v_ashrrev_i32_e32 v169, 31, v168
	v_lshlrev_b64 v[202:203], 1, v[168:169]
	v_ashrrev_i32_e32 v171, 31, v170
	v_or_b32_e32 v182, 16, v170
	v_lshl_add_u64 v[172:173], s[64:65], 0, v[202:203]
	v_lshlrev_b64 v[204:205], 11, v[170:171]
	v_ashrrev_i32_e32 v183, 31, v182
	v_or_b32_e32 v178, 32, v170
	v_lshl_add_u64 v[128:129], v[172:173], 0, v[204:205]
	v_lshlrev_b64 v[184:185], 11, v[182:183]
	v_ashrrev_i32_e32 v179, 31, v178
	v_or_b32_e32 v174, 48, v170
	global_load_dwordx4 v[194:197], v[128:129], off
	global_load_dwordx4 v[198:201], v[128:129], off offset:256
	v_lshl_add_u64 v[128:129], v[172:173], 0, v[184:185]
	v_lshlrev_b64 v[180:181], 11, v[178:179]
	v_ashrrev_i32_e32 v175, 31, v174
	global_load_dwordx4 v[148:151], v[128:129], off
	global_load_dwordx4 v[144:147], v[128:129], off offset:256
	v_lshl_add_u64 v[128:129], v[172:173], 0, v[180:181]
	v_lshlrev_b64 v[176:177], 11, v[174:175]
	global_load_dwordx4 v[140:143], v[128:129], off
	global_load_dwordx4 v[136:139], v[128:129], off offset:256
	v_lshl_add_u64 v[128:129], v[172:173], 0, v[176:177]
	global_load_dwordx4 v[132:135], v[128:129], off
	s_nop 0
	global_load_dwordx4 v[128:131], v[128:129], off offset:256
	s_lshl_b32 s14, s10, 2
	s_ashr_i32 s15, s14, 31
	v_add_u32_e32 v252, 0x80, v170
	v_ashrrev_i32_e32 v253, 31, v252
	v_lshlrev_b64 v[252:253], 11, v[252:253]
	v_lshl_add_u64 v[252:253], v[172:173], 0, v[252:253]
	global_load_dwordx4 v[236:239], v[252:253], off
	global_load_dwordx4 v[240:243], v[252:253], off offset:256
	v_add_u32_e32 v252, 0x90, v170
	v_ashrrev_i32_e32 v253, 31, v252
	v_lshlrev_b64 v[252:253], 11, v[252:253]
	v_lshl_add_u64 v[252:253], v[172:173], 0, v[252:253]
	global_load_dwordx4 v[244:247], v[252:253], off
	global_load_dwordx4 v[248:251], v[252:253], off offset:256
	v_add_u32_e32 v252, 0xa0, v170
	v_ashrrev_i32_e32 v253, 31, v252
	v_lshlrev_b64 v[252:253], 11, v[252:253]
	v_lshl_add_u64 v[252:253], v[172:173], 0, v[252:253]
	global_load_dwordx4 v[210:213], v[252:253], off
	global_load_dwordx4 v[214:217], v[252:253], off offset:256
	s_waitcnt vmcnt(6)
	v_lshlrev_b32_e32 v206, 16, v194
	v_and_b32_e32 v207, 0xffff0000, v194
	v_lshlrev_b32_e32 v194, 16, v195
	v_and_b32_e32 v195, 0xffff0000, v195
	v_lshlrev_b32_e32 v208, 16, v196
	v_and_b32_e32 v209, 0xffff0000, v196
	v_lshlrev_b32_e32 v196, 16, v197
	v_and_b32_e32 v197, 0xffff0000, v197
	v_pk_add_f32 v[126:127], v[126:127], v[194:195]
	v_pk_add_f32 v[124:125], v[124:125], v[206:207]
	v_pk_add_f32 v[194:195], v[122:123], v[196:197]
	v_pk_add_f32 v[122:123], v[120:121], v[208:209]
	v_mul_f32_e32 v120, v125, v125
	v_mul_f32_e32 v121, v127, v127
	v_fmac_f32_e32 v120, v124, v124
	v_fmac_f32_e32 v121, v126, v126
	v_add_f32_e32 v120, v120, v121
	v_mul_f32_e32 v121, v123, v123
	v_mul_f32_e32 v196, v195, v195
	v_fmac_f32_e32 v121, v122, v122
	v_fmac_f32_e32 v196, v194, v194
	v_add_f32_e32 v121, v121, v196
	v_add_f32_e32 v206, v120, v121
	v_cvt_pk_bf16_f32 v120, v124, v125
	v_cvt_pk_bf16_f32 v121, v126, v127
	v_lshlrev_b32_e32 v124, 16, v198
	v_and_b32_e32 v125, 0xffff0000, v198
	v_lshlrev_b32_e32 v126, 16, v199
	v_and_b32_e32 v127, 0xffff0000, v199
	v_cvt_pk_bf16_f32 v122, v122, v123
	v_cvt_pk_bf16_f32 v123, v194, v195
	v_lshlrev_b32_e32 v194, 16, v200
	v_and_b32_e32 v195, 0xffff0000, v200
	v_pk_add_f32 v[118:119], v[118:119], v[126:127]
	v_pk_add_f32 v[116:117], v[116:117], v[124:125]
	v_lshlrev_b32_e32 v196, 16, v201
	v_and_b32_e32 v197, 0xffff0000, v201
	v_pk_add_f32 v[126:127], v[112:113], v[194:195]
	v_mul_f32_e32 v112, v117, v117
	v_mul_f32_e32 v113, v119, v119
	v_pk_add_f32 v[124:125], v[114:115], v[196:197]
	v_fmac_f32_e32 v112, v116, v116
	v_fmac_f32_e32 v113, v118, v118
	v_add_f32_e32 v112, v112, v113
	v_mul_f32_e32 v113, v127, v127
	v_mul_f32_e32 v114, v125, v125
	v_fmac_f32_e32 v113, v126, v126
	v_fmac_f32_e32 v114, v124, v124
	v_add_f32_e32 v113, v113, v114
	v_add_f32_e32 v112, v112, v113
	v_and_b32_e32 v114, 64, v193
	v_add_f32_e32 v113, v206, v112
	v_xor_b32_e32 v112, 16, v193
	v_add_u32_e32 v196, 64, v114
	v_cmp_lt_i32_e32 vcc, v112, v196
	v_lshl_add_u64 v[114:115], s[64:65], 0, v[204:205]
	v_lshl_add_u64 v[194:195], v[114:115], 0, v[202:203]
	v_cndmask_b32_e32 v112, v193, v112, vcc
	v_lshlrev_b32_e32 v112, 2, v112
	ds_bpermute_b32 v197, v112, v113
	global_store_dwordx4 v[194:195], v[120:123], off
	v_cvt_pk_bf16_f32 v116, v116, v117
	v_cvt_pk_bf16_f32 v117, v118, v119
	v_cvt_pk_bf16_f32 v118, v126, v127
	s_waitcnt lgkmcnt(0)
	v_add_f32_e32 v114, v113, v197
	v_xor_b32_e32 v113, 32, v193
	v_cmp_lt_i32_e32 vcc, v113, v196
	v_cvt_pk_bf16_f32 v119, v124, v125
	global_store_dwordx4 v[194:195], v[116:119], off offset:256
	s_nop 0
	v_cndmask_b32_e32 v113, v193, v113, vcc
	v_lshlrev_b32_e32 v113, 2, v113
	ds_bpermute_b32 v115, v113, v114
	s_and_saveexec_b64 s[16:17], s[2:3]
	s_cbranch_execz .LBB0_1744
	s_waitcnt lgkmcnt(0)
	v_add_f32_e32 v116, v114, v115
	v_lshlrev_b64 v[114:115], 6, v[170:171]
	v_lshl_add_u64 v[114:115], s[74:75], 0, v[114:115]
	v_lshl_add_u64 v[114:115], s[14:15], 2, v[114:115]
	s_lshl_b32 s10, s34, 2
	v_lshl_add_u64 v[114:115], v[114:115], 0, s[10:11]
	global_store_dword v[114:115], v116, off

.LBB0_1750:
	s_or_b64 exec, exec, s[16:17]
	v_add_u32_e32 v100, 0x80, v170
	v_ashrrev_i32_e32 v101, 31, v100
	v_add_u32_e32 v96, 0x90, v170
	v_lshlrev_b64 v[110:111], 11, v[100:101]
	v_ashrrev_i32_e32 v97, 31, v96
	v_add_u32_e32 v92, 0xa0, v170
	s_waitcnt lgkmcnt(0)
	v_lshl_add_u64 v[64:65], v[172:173], 0, v[110:111]
	v_lshlrev_b64 v[98:99], 11, v[96:97]
	v_ashrrev_i32_e32 v93, 31, v92
	v_add_u32_e32 v88, 0xb0, v170
	v_lshl_add_u64 v[64:65], v[172:173], 0, v[98:99]
	v_lshlrev_b64 v[94:95], 11, v[92:93]
	v_ashrrev_i32_e32 v89, 31, v88
	v_lshl_add_u64 v[64:65], v[172:173], 0, v[94:95]
	v_lshlrev_b64 v[90:91], 11, v[88:89]
	v_lshl_add_u64 v[64:65], v[172:173], 0, v[90:91]
	global_load_dwordx4 v[68:71], v[64:65], off
	s_nop 0
	global_load_dwordx4 v[64:67], v[64:65], off offset:256
	s_waitcnt vmcnt(15)
	v_lshlrev_b32_e32 v114, 16, v236
	v_and_b32_e32 v115, 0xffff0000, v236
	v_lshlrev_b32_e32 v236, 16, v237
	v_and_b32_e32 v237, 0xffff0000, v237
	v_lshlrev_b32_e32 v116, 16, v238
	v_and_b32_e32 v117, 0xffff0000, v238
	v_lshlrev_b32_e32 v238, 16, v239
	v_and_b32_e32 v239, 0xffff0000, v239
	v_pk_add_f32 v[62:63], v[62:63], v[236:237]
	v_pk_add_f32 v[60:61], v[60:61], v[114:115]
	v_pk_add_f32 v[236:237], v[58:59], v[238:239]
	v_pk_add_f32 v[58:59], v[56:57], v[116:117]
	v_mul_f32_e32 v56, v61, v61
	v_mul_f32_e32 v57, v63, v63
	v_fmac_f32_e32 v56, v60, v60
	v_fmac_f32_e32 v57, v62, v62
	v_add_f32_e32 v56, v56, v57
	v_mul_f32_e32 v57, v59, v59
	v_mul_f32_e32 v238, v237, v237
	v_fmac_f32_e32 v57, v58, v58
	v_fmac_f32_e32 v238, v236, v236
	v_add_f32_e32 v57, v57, v238
	v_add_f32_e32 v114, v56, v57
	v_cvt_pk_bf16_f32 v56, v60, v61
	v_cvt_pk_bf16_f32 v57, v62, v63
	s_waitcnt vmcnt(14)
	v_lshlrev_b32_e32 v60, 16, v240
	v_and_b32_e32 v61, 0xffff0000, v240
	v_lshlrev_b32_e32 v62, 16, v241
	v_and_b32_e32 v63, 0xffff0000, v241
	v_cvt_pk_bf16_f32 v58, v58, v59
	v_cvt_pk_bf16_f32 v59, v236, v237
	v_lshlrev_b32_e32 v236, 16, v242
	v_and_b32_e32 v237, 0xffff0000, v242
	v_pk_add_f32 v[54:55], v[54:55], v[62:63]
	v_pk_add_f32 v[52:53], v[52:53], v[60:61]
	v_lshlrev_b32_e32 v238, 16, v243
	v_and_b32_e32 v239, 0xffff0000, v243
	v_pk_add_f32 v[62:63], v[48:49], v[236:237]
	v_mul_f32_e32 v48, v53, v53
	v_mul_f32_e32 v49, v55, v55
	v_pk_add_f32 v[60:61], v[50:51], v[238:239]
	v_fmac_f32_e32 v48, v52, v52
	v_fmac_f32_e32 v49, v54, v54
	v_add_f32_e32 v48, v48, v49
	v_mul_f32_e32 v49, v63, v63
	v_mul_f32_e32 v50, v61, v61
	v_fmac_f32_e32 v49, v62, v62
	v_fmac_f32_e32 v50, v60, v60
	v_add_f32_e32 v49, v49, v50
	v_add_f32_e32 v48, v48, v49
	v_add_f32_e32 v51, v114, v48
	ds_bpermute_b32 v238, v112, v51
	v_lshl_add_u64 v[48:49], s[64:65], 0, v[110:111]
	v_lshl_add_u64 v[236:237], v[168:169], 1, v[48:49]
	global_store_dwordx4 v[236:237], v[56:59], off
	v_cvt_pk_bf16_f32 v50, v52, v53
	s_waitcnt lgkmcnt(0)
	v_add_f32_e32 v48, v51, v238
	ds_bpermute_b32 v49, v113, v48
	v_cvt_pk_bf16_f32 v51, v54, v55
	v_cvt_pk_bf16_f32 v52, v62, v63
	v_cvt_pk_bf16_f32 v53, v60, v61
	global_store_dwordx4 v[236:237], v[50:53], off offset:256
	s_and_saveexec_b64 s[16:17], s[2:3]
	s_cbranch_execz .LBB0_1752
	s_waitcnt lgkmcnt(0)
	v_add_f32_e32 v50, v48, v49
	v_lshlrev_b64 v[48:49], 6, v[100:101]
	v_lshl_add_u64 v[48:49], s[74:75], 0, v[48:49]
	v_lshl_add_u64 v[48:49], s[14:15], 2, v[48:49]
	s_lshl_b32 s10, s34, 2
	v_lshl_add_u64 v[48:49], v[48:49], 0, s[10:11]
	global_store_dword v[48:49], v50, off
.LBB0_1752:
	s_or_b64 exec, exec, s[16:17]
	s_waitcnt vmcnt(15)
	v_lshlrev_b32_e32 v48, 16, v244
	s_waitcnt lgkmcnt(0)
	v_and_b32_e32 v49, 0xffff0000, v244
	v_lshlrev_b32_e32 v50, 16, v245
	v_and_b32_e32 v51, 0xffff0000, v245
	v_lshlrev_b32_e32 v52, 16, v246
	v_and_b32_e32 v53, 0xffff0000, v246
	v_lshlrev_b32_e32 v54, 16, v247
	v_and_b32_e32 v55, 0xffff0000, v247
	v_pk_add_f32 v[46:47], v[46:47], v[50:51]
	v_pk_add_f32 v[44:45], v[44:45], v[48:49]
	v_pk_add_f32 v[48:49], v[42:43], v[54:55]
	v_pk_add_f32 v[42:43], v[40:41], v[52:53]
	v_mul_f32_e32 v40, v45, v45
	v_mul_f32_e32 v41, v47, v47
	v_fmac_f32_e32 v40, v44, v44
	v_fmac_f32_e32 v41, v46, v46
	v_add_f32_e32 v40, v40, v41
	v_mul_f32_e32 v41, v43, v43
	v_mul_f32_e32 v50, v49, v49
	v_fmac_f32_e32 v41, v42, v42
	v_fmac_f32_e32 v50, v48, v48
	v_add_f32_e32 v41, v41, v50
	v_add_f32_e32 v52, v40, v41
	v_cvt_pk_bf16_f32 v40, v44, v45
	v_cvt_pk_bf16_f32 v41, v46, v47
	s_waitcnt vmcnt(14)
	v_lshlrev_b32_e32 v44, 16, v248
	v_and_b32_e32 v45, 0xffff0000, v248
	v_lshlrev_b32_e32 v46, 16, v249
	v_and_b32_e32 v47, 0xffff0000, v249
	v_cvt_pk_bf16_f32 v42, v42, v43
	v_cvt_pk_bf16_f32 v43, v48, v49
	v_lshlrev_b32_e32 v48, 16, v250
	v_and_b32_e32 v49, 0xffff0000, v250
	v_pk_add_f32 v[38:39], v[38:39], v[46:47]
	v_pk_add_f32 v[36:37], v[36:37], v[44:45]
	v_lshlrev_b32_e32 v50, 16, v251
	v_and_b32_e32 v51, 0xffff0000, v251
	v_pk_add_f32 v[46:47], v[32:33], v[48:49]
	v_mul_f32_e32 v32, v37, v37
	v_mul_f32_e32 v33, v39, v39
	v_pk_add_f32 v[44:45], v[34:35], v[50:51]
	v_fmac_f32_e32 v32, v36, v36
	v_fmac_f32_e32 v33, v38, v38
	v_add_f32_e32 v32, v32, v33
	v_mul_f32_e32 v33, v47, v47
	v_mul_f32_e32 v34, v45, v45
	v_fmac_f32_e32 v33, v46, v46
	v_fmac_f32_e32 v34, v44, v44
	v_add_f32_e32 v33, v33, v34
	v_add_f32_e32 v32, v32, v33
	v_add_f32_e32 v35, v52, v32
	ds_bpermute_b32 v50, v112, v35
	v_lshl_add_u64 v[32:33], s[64:65], 0, v[98:99]
	v_lshl_add_u64 v[48:49], v[168:169], 1, v[32:33]
	global_store_dwordx4 v[48:49], v[40:43], off
	v_cvt_pk_bf16_f32 v34, v36, v37
	s_waitcnt lgkmcnt(0)
	v_add_f32_e32 v32, v35, v50
	ds_bpermute_b32 v33, v113, v32
	v_cvt_pk_bf16_f32 v35, v38, v39
	v_cvt_pk_bf16_f32 v36, v46, v47
	v_cvt_pk_bf16_f32 v37, v44, v45
	global_store_dwordx4 v[48:49], v[34:37], off offset:256
	s_and_saveexec_b64 s[16:17], s[2:3]
	s_cbranch_execz .LBB0_1754
	s_waitcnt lgkmcnt(0)
	v_add_f32_e32 v34, v32, v33
	v_lshlrev_b64 v[32:33], 6, v[96:97]
	v_lshl_add_u64 v[32:33], s[74:75], 0, v[32:33]
	v_lshl_add_u64 v[32:33], s[14:15], 2, v[32:33]
	s_lshl_b32 s10, s34, 2
	v_lshl_add_u64 v[32:33], v[32:33], 0, s[10:11]
	global_store_dword v[32:33], v34, off
.LBB0_1754:
	s_or_b64 exec, exec, s[16:17]
	s_waitcnt vmcnt(15)
	v_lshlrev_b32_e32 v32, 16, v210
	s_waitcnt lgkmcnt(0)
	v_and_b32_e32 v33, 0xffff0000, v210
	v_lshlrev_b32_e32 v34, 16, v211
	v_and_b32_e32 v35, 0xffff0000, v211
	v_lshlrev_b32_e32 v36, 16, v212
	v_and_b32_e32 v37, 0xffff0000, v212
	v_lshlrev_b32_e32 v38, 16, v213
	v_and_b32_e32 v39, 0xffff0000, v213
	v_pk_add_f32 v[30:31], v[30:31], v[34:35]
	v_pk_add_f32 v[28:29], v[28:29], v[32:33]
	v_pk_add_f32 v[32:33], v[26:27], v[38:39]
	v_pk_add_f32 v[26:27], v[24:25], v[36:37]
	v_mul_f32_e32 v24, v29, v29
	v_mul_f32_e32 v25, v31, v31
	v_fmac_f32_e32 v24, v28, v28
	v_fmac_f32_e32 v25, v30, v30
	v_add_f32_e32 v24, v24, v25
	v_mul_f32_e32 v25, v27, v27
	v_mul_f32_e32 v34, v33, v33
	v_fmac_f32_e32 v25, v26, v26
	v_fmac_f32_e32 v34, v32, v32
	v_add_f32_e32 v25, v25, v34
	v_add_f32_e32 v36, v24, v25
	v_cvt_pk_bf16_f32 v24, v28, v29
	v_cvt_pk_bf16_f32 v25, v30, v31
	s_waitcnt vmcnt(14)
	v_lshlrev_b32_e32 v28, 16, v214
	v_and_b32_e32 v29, 0xffff0000, v214
	v_lshlrev_b32_e32 v30, 16, v215
	v_and_b32_e32 v31, 0xffff0000, v215
	v_cvt_pk_bf16_f32 v26, v26, v27
	v_cvt_pk_bf16_f32 v27, v32, v33
	v_lshlrev_b32_e32 v32, 16, v216
	v_and_b32_e32 v33, 0xffff0000, v216
	v_pk_add_f32 v[22:23], v[22:23], v[30:31]
	v_pk_add_f32 v[20:21], v[20:21], v[28:29]
	v_lshlrev_b32_e32 v34, 16, v217
	v_and_b32_e32 v35, 0xffff0000, v217
	v_pk_add_f32 v[30:31], v[16:17], v[32:33]
	v_mul_f32_e32 v16, v21, v21
	v_mul_f32_e32 v17, v23, v23
	v_pk_add_f32 v[28:29], v[18:19], v[34:35]
	v_fmac_f32_e32 v16, v20, v20
	v_fmac_f32_e32 v17, v22, v22
	v_add_f32_e32 v16, v16, v17
	v_mul_f32_e32 v17, v31, v31
	v_mul_f32_e32 v18, v29, v29
	v_fmac_f32_e32 v17, v30, v30
	v_fmac_f32_e32 v18, v28, v28
	v_add_f32_e32 v17, v17, v18
	v_add_f32_e32 v16, v16, v17
	v_add_f32_e32 v19, v36, v16
	ds_bpermute_b32 v34, v112, v19
	v_lshl_add_u64 v[16:17], s[64:65], 0, v[94:95]
	v_lshl_add_u64 v[32:33], v[168:169], 1, v[16:17]
	global_store_dwordx4 v[32:33], v[24:27], off
	v_cvt_pk_bf16_f32 v18, v20, v21
	s_waitcnt lgkmcnt(0)
	v_add_f32_e32 v16, v19, v34
	ds_bpermute_b32 v17, v113, v16
	v_cvt_pk_bf16_f32 v19, v22, v23
	v_cvt_pk_bf16_f32 v20, v30, v31
	v_cvt_pk_bf16_f32 v21, v28, v29
	global_store_dwordx4 v[32:33], v[18:21], off offset:256
	s_and_saveexec_b64 s[16:17], s[2:3]
	s_cbranch_execz .LBB0_1756
	s_waitcnt lgkmcnt(0)
	v_add_f32_e32 v18, v16, v17
	v_lshlrev_b64 v[16:17], 6, v[92:93]
	v_lshl_add_u64 v[16:17], s[74:75], 0, v[16:17]
	v_lshl_add_u64 v[16:17], s[14:15], 2, v[16:17]
	s_lshl_b32 s10, s34, 2
	v_lshl_add_u64 v[16:17], v[16:17], 0, s[10:11]
	global_store_dword v[16:17], v18, off
